# 8-byte alignment of every 8-byte instruction in the hand-written attention loop and P8/P10 epilogues (s_nop 0 / e64 re-encoding), K-loop heads pinned at fixed byte phases
# speedup vs baseline: 1.0030x; 1.0030x over previous
; __device__ __forceinline__ void attn_phase(LAS unsigned char* lds, const bf16_t* __restrict__ Q, const bf16_t* __restrict__ KN, const bf16_t* __restrict__ KR,
;                                            const bf16_t* __restrict__ VT, bf16_t* AO, int vcu, int G, int tid, int lane, int wave) {
;     ...
;             for (int t = 0; t < NT2; ++t) {
;                 const bool more = (t + 1 < NT2);
.Lat_step:
	s_add_i32 s39, s8, 1
	s_bitcmp1_b32 s8, 0
	s_cselect_b32 s37, 0xac00, 0
	s_cselect_b32 s38, 0, 0xac00
	s_nop 0
	s_cmp_lt_u32 s39, s36
	s_cbranch_scc0 .Lat_nopf
	s_mov_b32 s40, s39
	s_mov_b32 s41, 0
	s_lshl_b64 s[14:15], s[40:41], 17
	s_add_u32 s14, s10, s14
	s_addc_u32 s15, s11, s15
	global_load_dwordx4 v[228:231], v198, s[14:15]
	s_add_u32 s14, s14, 0x10000
	s_nop 0
	s_addc_u32 s15, s15, 0
	global_load_dwordx4 v[232:235], v198, s[14:15]
	s_nop 0
	s_lshl_b64 s[14:15], s[40:41], 13
	v_lshl_add_u64 v[250:251], v[208:209], 0, s[14:15]
	s_nop 0
	s_lshl_b64 s[14:15], s[40:41], 8
	v_lshl_add_u64 v[252:253], v[210:211], 0, s[14:15]
	global_load_dwordx4 v[236:239], v[250:251], off
	global_load_dwordx4 v[240:243], v[252:253], off
	global_load_dwordx4 v[244:247], v[252:253], off offset:128

; #define LAS __attribute__((address_space(3)))
; __device__ __forceinline__ void attn_phase(LAS unsigned char* lds, const bf16_t* __restrict__ Q, const bf16_t* __restrict__ KN, const bf16_t* __restrict__ KR,
;                                            const bf16_t* __restrict__ VT, bf16_t* AO, int vcu, int G, int tid, int lane, int wave) {
;     ...
;                 const LAS unsigned char* kA = buf + (pr * KP + 8 * hi) * 2; const LAS unsigned char* vA = buf + KBUF + (r32 * VP + 8 * hi) * 2;
;                 if (2 * t + 1 <= qc) {
;                     bf16x8 kf[12], kf2[12], vf[8], vf2[8], pa[4], pb2[4]; f32x16 a0, a1, b0, b1;
;                     attn_ldk(kf, kA);
;                     __builtin_amdgcn_sched_barrier(0);
;                     attn_qk(a0, a1, kf, qf);
;                     attn_ldk(kf2, kA + 64 * KP * 2);
;                     __builtin_amdgcn_sched_barrier(0);
;                     attn_qk(b0, b1, kf2, qf);
.Lat_both:
	v_add_u32_e32 v1, s37, v222
	v_add_u32_e32 v225, s37, v223
	ds_read_b128 v[138:141], v1
	ds_read_b128 v[142:145], v1 offset:6656
	ds_read_b128 v[146:149], v1 offset:32
	ds_read_b128 v[150:153], v1 offset:6688
	ds_read_b128 v[154:157], v1 offset:64
	ds_read_b128 v[158:161], v1 offset:6720
	ds_read_b128 v[162:165], v1 offset:96
	ds_read_b128 v[166:169], v1 offset:6752
	s_waitcnt vmcnt(5)
	s_waitcnt lgkmcnt(7)
	v_mfma_f32_32x32x16_bf16 v[34:49], v[138:141], v[114:117], v[98:113]
	ds_read_b128 v[138:141], v1 offset:128
	s_nop 0
	s_waitcnt lgkmcnt(7)
	v_mfma_f32_32x32x16_bf16 v[50:65], v[142:145], v[114:117], v[98:113]
	ds_read_b128 v[142:145], v1 offset:6784
	s_nop 0
	s_waitcnt lgkmcnt(7)
	v_mfma_f32_32x32x16_bf16 v[34:49], v[146:149], v[118:121], v[34:49]
	ds_read_b128 v[146:149], v1 offset:160
	s_nop 0
	s_waitcnt lgkmcnt(7)
	v_mfma_f32_32x32x16_bf16 v[50:65], v[150:153], v[118:121], v[50:65]
	ds_read_b128 v[150:153], v1 offset:6816
	s_nop 0
	s_waitcnt lgkmcnt(7)
	v_mfma_f32_32x32x16_bf16 v[34:49], v[154:157], v[122:125], v[34:49]
	ds_read_b128 v[154:157], v1 offset:13312
	s_nop 0
	s_waitcnt lgkmcnt(7)
	v_mfma_f32_32x32x16_bf16 v[50:65], v[158:161], v[122:125], v[50:65]
	ds_read_b128 v[158:161], v1 offset:19968
	s_nop 0
	s_waitcnt lgkmcnt(7)
	v_mfma_f32_32x32x16_bf16 v[34:49], v[162:165], v[126:129], v[34:49]
	ds_read_b128 v[162:165], v1 offset:13344
	s_nop 0
	s_waitcnt lgkmcnt(7)
	v_mfma_f32_32x32x16_bf16 v[50:65], v[166:169], v[126:129], v[50:65]
	ds_read_b128 v[166:169], v1 offset:20000
	s_nop 0
	s_waitcnt lgkmcnt(7)
	v_mfma_f32_32x32x16_bf16 v[34:49], v[138:141], v[130:133], v[34:49]
	ds_read_b128 v[138:141], v1 offset:13376
	s_nop 0
	s_waitcnt lgkmcnt(7)
	v_mfma_f32_32x32x16_bf16 v[50:65], v[142:145], v[130:133], v[50:65]
	ds_read_b128 v[142:145], v1 offset:20032
	s_nop 0
	s_waitcnt lgkmcnt(7)
	v_mfma_f32_32x32x16_bf16 v[34:49], v[146:149], v[134:137], v[34:49]
	ds_read_b128 v[146:149], v1 offset:13408
	s_nop 0
	s_waitcnt lgkmcnt(7)
	v_mfma_f32_32x32x16_bf16 v[50:65], v[150:153], v[134:137], v[50:65]
	ds_read_b128 v[150:153], v1 offset:20064
	s_nop 0
	s_waitcnt lgkmcnt(7)
	v_mfma_f32_32x32x16_bf16 v[66:81], v[154:157], v[114:117], v[98:113]
	ds_read_b128 v[154:157], v1 offset:13440
	s_nop 0
	s_waitcnt lgkmcnt(7)
	v_mfma_f32_32x32x16_bf16 v[82:97], v[158:161], v[114:117], v[98:113]
	ds_read_b128 v[158:161], v1 offset:20096
	s_nop 0
	s_waitcnt lgkmcnt(7)
	v_mfma_f32_32x32x16_bf16 v[66:81], v[162:165], v[118:121], v[66:81]
	ds_read_b128 v[162:165], v1 offset:13472
	s_nop 0
	s_waitcnt lgkmcnt(7)
	v_mfma_f32_32x32x16_bf16 v[82:97], v[166:169], v[118:121], v[82:97]
	ds_read_b128 v[166:169], v1 offset:20128
	s_nop 0
	s_waitcnt lgkmcnt(7)
	v_mfma_f32_32x32x16_bf16 v[66:81], v[138:141], v[122:125], v[66:81]
	ds_read_b128 v[170:173], v225 offset:26624
	s_nop 0
	s_waitcnt lgkmcnt(7)
	v_mfma_f32_32x32x16_bf16 v[82:97], v[142:145], v[122:125], v[82:97]
	ds_read_b128 v[174:177], v225 offset:35328
	s_nop 0
	s_waitcnt lgkmcnt(7)
	v_mfma_f32_32x32x16_bf16 v[66:81], v[146:149], v[126:129], v[66:81]
	ds_read_b128 v[178:181], v225 offset:26656
	s_nop 0
	s_waitcnt lgkmcnt(7)
	v_mfma_f32_32x32x16_bf16 v[82:97], v[150:153], v[126:129], v[82:97]
	ds_read_b128 v[182:185], v225 offset:35360
	s_nop 0
	s_waitcnt lgkmcnt(7)
	v_mfma_f32_32x32x16_bf16 v[66:81], v[154:157], v[130:133], v[66:81]
	ds_read_b128 v[186:189], v225 offset:26688
	s_nop 0
	s_waitcnt lgkmcnt(7)
	v_mfma_f32_32x32x16_bf16 v[82:97], v[158:161], v[130:133], v[82:97]
	ds_read_b128 v[190:193], v225 offset:35392
	s_nop 0
	s_waitcnt lgkmcnt(7)
	v_mfma_f32_32x32x16_bf16 v[66:81], v[162:165], v[134:137], v[66:81]
	s_nop 0
	s_waitcnt lgkmcnt(6)
	v_mfma_f32_32x32x16_bf16 v[82:97], v[166:169], v[134:137], v[82:97]
	s_mov_b32 s41, 0
	s_cmp_lg_u32 s7, 0
	s_cbranch_scc1 .Lat_first_A2
; #define LAS __attribute__((address_space(3)))
; __device__ __forceinline__ void attn_phase(LAS unsigned char* lds, const bf16_t* __restrict__ Q, const bf16_t* __restrict__ KN, const bf16_t* __restrict__ KR,
;                                            const bf16_t* __restrict__ VT, bf16_t* AO, int vcu, int G, int tid, int lane, int wave) {
;     ...
;                     attn_softmax(a0, a1, pa, o0, o1, m_run, l_run);
;                     attn_ldv(vf, vA);
;                     __builtin_amdgcn_sched_barrier(0);
;                     PREFETCH_NEXT();
;                     attn_ldv(vf2, vA + 128);
;                     __builtin_amdgcn_sched_barrier(0);
;                     attn_pv(vf, pa, o0, o1);
;                     attn_softmax(b0, b1, pb2, o0, o1, m_run, l_run);
;                     __builtin_amdgcn_sched_barrier(0);
;                     attn_pv(vf2, pb2, o0, o1);
;     ...
;                 if (more) { LAS unsigned char* nb = lds + ((t + 1) & 1) * BUF;
;                     *(LAS u32x4*)(nb + kdst) = gk0; *(LAS u32x4*)(nb + kdst + 64 * KP * 2) = gk1; *(LAS u32x4*)(nb + rdst) = gr; *(LAS u32x4*)(nb + vdst) = gv0; *(LAS u32x4*)(nb + vdst + 128) = gv1; }
.Lat_exp_A2:
	v_exp_f32_e32 v34, v34
	v_exp_f32_e32 v50, v50
	v_exp_f32_e32 v35, v35
	v_exp_f32_e32 v51, v51
	v_exp_f32_e32 v36, v36
	v_exp_f32_e32 v52, v52
	v_exp_f32_e32 v37, v37
	v_exp_f32_e32 v53, v53
	v_exp_f32_e32 v38, v38
	v_exp_f32_e32 v54, v54
	v_exp_f32_e32 v39, v39
	v_exp_f32_e32 v55, v55
	v_exp_f32_e32 v40, v40
	v_exp_f32_e32 v56, v56
	v_exp_f32_e32 v41, v41
	v_exp_f32_e32 v57, v57
	v_exp_f32_e32 v42, v42
	v_exp_f32_e32 v58, v58
	v_exp_f32_e32 v43, v43
	v_exp_f32_e32 v59, v59
	v_exp_f32_e32 v44, v44
	v_exp_f32_e32 v60, v60
	v_exp_f32_e32 v45, v45
	v_exp_f32_e32 v61, v61
	v_exp_f32_e32 v46, v46
	v_exp_f32_e32 v62, v62
	v_exp_f32_e32 v47, v47
	v_exp_f32_e32 v63, v63
	v_exp_f32_e32 v48, v48
	v_exp_f32_e32 v64, v64
	v_exp_f32_e32 v49, v49
	v_exp_f32_e64 v65, v65
	v_pk_add_f32 v[250:251], v[34:35], v[36:37]
	v_pk_add_f32 v[252:253], v[50:51], v[52:53]
	v_pk_add_f32 v[250:251], v[250:251], v[38:39]
	v_pk_add_f32 v[252:253], v[252:253], v[54:55]
	v_pk_add_f32 v[250:251], v[250:251], v[40:41]
	v_pk_add_f32 v[252:253], v[252:253], v[56:57]
	v_pk_add_f32 v[250:251], v[250:251], v[42:43]
	v_pk_add_f32 v[252:253], v[252:253], v[58:59]
	v_pk_add_f32 v[250:251], v[250:251], v[44:45]
	v_pk_add_f32 v[252:253], v[252:253], v[60:61]
	v_pk_add_f32 v[250:251], v[250:251], v[46:47]
	v_pk_add_f32 v[252:253], v[252:253], v[62:63]
	v_pk_add_f32 v[250:251], v[250:251], v[48:49]
	v_pk_add_f32 v[252:253], v[252:253], v[64:65]
	v_pk_add_f32 v[250:251], v[250:251], v[252:253]
	v_add_f32_e32 v1, v250, v251
	v_cmp_lt_f32_e32 vcc, s26, v1
	s_cbranch_vccnz .Lat_rare_A2
.Lat_fast_A2:
	v_add_f32_e32 v227, v227, v1
	v_cvt_pk_bf16_f32 v34, v34, v35
	v_cvt_pk_bf16_f32 v35, v36, v37
	v_cvt_pk_bf16_f32 v36, v38, v39
	v_cvt_pk_bf16_f32 v37, v40, v41
	v_cvt_pk_bf16_f32 v42, v42, v43
	v_cvt_pk_bf16_f32 v43, v44, v45
	v_cvt_pk_bf16_f32 v44, v46, v47
	v_cvt_pk_bf16_f32 v45, v48, v49
	v_cvt_pk_bf16_f32 v50, v50, v51
	v_cvt_pk_bf16_f32 v51, v52, v53
	v_cvt_pk_bf16_f32 v52, v54, v55
	v_cvt_pk_bf16_f32 v53, v56, v57
	v_cvt_pk_bf16_f32 v58, v58, v59
	v_cvt_pk_bf16_f32 v59, v60, v61
	v_cvt_pk_bf16_f32 v60, v62, v63
	v_cvt_pk_bf16_f32 v61, v64, v65
	s_nop 0
	s_waitcnt lgkmcnt(5)
	v_mfma_f32_32x32x16_bf16 v[2:17], v[170:173], v[34:37], v[2:17]
	ds_read_b128 v[170:173], v225 offset:26720
	s_nop 0
	s_waitcnt lgkmcnt(5)
	v_mfma_f32_32x32x16_bf16 v[18:33], v[174:177], v[34:37], v[18:33]
	ds_read_b128 v[174:177], v225 offset:35424
	s_waitcnt vmcnt(0)
	v_add_u32_e32 v226, s38, v219
	ds_write_b128 v226, v[228:231]
	s_nop 0
	s_waitcnt lgkmcnt(6)
	v_mfma_f32_32x32x16_bf16 v[2:17], v[178:181], v[42:45], v[2:17]
	ds_read_b128 v[178:181], v225 offset:26752
	ds_write_b128 v226, v[232:235] offset:13312
	s_nop 0
	s_waitcnt lgkmcnt(7)
	v_mfma_f32_32x32x16_bf16 v[18:33], v[182:185], v[42:45], v[18:33]
	ds_read_b128 v[182:185], v225 offset:35456
	v_add_u32_e64 v226, s38, v220
	ds_write_b128 v226, v[236:239]
	s_nop 0
	s_waitcnt lgkmcnt(8)
	v_mfma_f32_32x32x16_bf16 v[2:17], v[186:189], v[50:53], v[2:17]
	ds_read_b128 v[186:189], v225 offset:26784
	v_add_u32_e64 v226, s38, v221
	ds_write_b128 v226, v[240:243] offset:26624
	s_nop 0
	s_waitcnt lgkmcnt(9)
	v_mfma_f32_32x32x16_bf16 v[18:33], v[190:193], v[50:53], v[18:33]
	ds_read_b128 v[190:193], v225 offset:35488
	ds_write_b128 v226, v[244:247] offset:26752
	s_nop 0
	s_waitcnt lgkmcnt(10)
	v_mfma_f32_32x32x16_bf16 v[2:17], v[170:173], v[58:61], v[2:17]
	ds_read_b128 v[170:173], v225 offset:26816
	s_nop 0
	s_waitcnt lgkmcnt(10)
	v_mfma_f32_32x32x16_bf16 v[18:33], v[174:177], v[58:61], v[18:33]
	ds_read_b128 v[174:177], v225 offset:35520
	s_cmp_lg_u32 s6, 0
	s_cbranch_scc1 .Lat_fix_B

; __device__ __forceinline__ unsigned pk2(float lo, float hi) { f32x2_t v = {lo, hi}; bf16x2_t b = __builtin_convertvector(v, bf16x2_t); return __builtin_bit_cast(unsigned, b); }
; __device__ __forceinline__ float max3f(float a, float b, float c) { return fmaxf(fmaxf(a, b), c); }
; __device__ __forceinline__ void attn_softmax(f32x16& p0, f32x16& p1, bf16x8 (&pb)[4], f32x16& o0, f32x16& o1, float& m_run, float& l_run) {
;     float mx = max3f(p0[0], p0[1], p1[0]), my = max3f(p0[2], p0[3], p1[1]);
;     mx = max3f(mx, p1[2], p1[3]);
; #pragma unroll
;     for (int r = 4; r < 16; r += 4) { mx = max3f(mx, p0[r], p0[r + 1]); my = max3f(my, p0[r + 2], p0[r + 3]); mx = max3f(mx, p1[r], p1[r + 1]); my = max3f(my, p1[r + 2], p1[r + 3]); }
;     mx = fmaxf(mx, my);
;     { auto rr = __builtin_amdgcn_permlane32_swap(__float_as_uint(mx), __float_as_uint(mx), false, false); mx = fmaxf(__uint_as_float(rr[0]), __uint_as_float(rr[1])); }
;     const float m_new = fmaxf(m_run, mx);
;     const float alpha = __builtin_amdgcn_exp2f(m_run - m_new);
;     m_run = m_new;
;     p0 = p0 - m_new; p1 = p1 - m_new;
; #pragma unroll
;     for (int r = 0; r < 16; ++r) { p0[r] = __builtin_amdgcn_exp2f(p0[r]); p1[r] = __builtin_amdgcn_exp2f(p1[r]); }
;     f32x16 sm = p0 + p1;
;     f32x2v s2 = (f32x2v){sm[0], sm[1]} + (f32x2v){sm[2], sm[3]};
; #pragma unroll
;     for (int r = 4; r < 16; r += 2) s2 += (f32x2v){sm[r], sm[r + 1]};
;     l_run = l_run * alpha + (s2[0] + s2[1]);
;     o0 = o0 * alpha; o1 = o1 * alpha;
; #pragma unroll
;     for (int s = 0; s < 2; ++s) {
;         u32x4 w; w.x = pk2(p0[8 * s], p0[8 * s + 1]); w.y = pk2(p0[8 * s + 2], p0[8 * s + 3]); w.z = pk2(p0[8 * s + 4], p0[8 * s + 5]); w.w = pk2(p0[8 * s + 6], p0[8 * s + 7]);
;         pb[s] = __builtin_bit_cast(bf16x8, w);
;         u32x4 w2; w2.x = pk2(p1[8 * s], p1[8 * s + 1]); w2.y = pk2(p1[8 * s + 2], p1[8 * s + 3]); w2.z = pk2(p1[8 * s + 4], p1[8 * s + 5]); w2.w = pk2(p1[8 * s + 6], p1[8 * s + 7]);
;         pb[2 + s] = __builtin_bit_cast(bf16x8, w2);
;     }
; }
; __device__ __forceinline__ void attn_pv(const bf16x8 (&vf)[8], const bf16x8 (&pb)[4], f32x16& o0, f32x16& o1) {
; #pragma unroll
;     for (int s = 0; s < 4; ++s) {
;         o0 = __builtin_amdgcn_mfma_f32_32x32x16_bf16(vf[2 * s], pb[s], o0, 0, 0, 0);
;         o1 = __builtin_amdgcn_mfma_f32_32x32x16_bf16(vf[2 * s + 1], pb[s], o1, 0, 0, 0);
;     }
; }
.Lat_exp_B2:
	v_exp_f32_e32 v66, v66
	v_exp_f32_e32 v82, v82
	v_exp_f32_e32 v67, v67
	v_exp_f32_e32 v83, v83
	v_exp_f32_e32 v68, v68
	v_exp_f32_e32 v84, v84
	v_exp_f32_e32 v69, v69
	v_exp_f32_e32 v85, v85
	v_exp_f32_e32 v70, v70
	v_exp_f32_e32 v86, v86
	v_exp_f32_e32 v71, v71
	v_exp_f32_e32 v87, v87
	v_exp_f32_e32 v72, v72
	v_exp_f32_e32 v88, v88
	v_exp_f32_e32 v73, v73
	v_exp_f32_e32 v89, v89
	v_exp_f32_e32 v74, v74
	v_exp_f32_e32 v90, v90
	v_exp_f32_e32 v75, v75
	v_exp_f32_e32 v91, v91
	v_exp_f32_e32 v76, v76
	v_exp_f32_e32 v92, v92
	v_exp_f32_e32 v77, v77
	v_exp_f32_e32 v93, v93
	v_exp_f32_e32 v78, v78
	v_exp_f32_e32 v94, v94
	v_exp_f32_e32 v79, v79
	v_exp_f32_e32 v95, v95
	v_exp_f32_e32 v80, v80
	v_exp_f32_e32 v96, v96
	v_exp_f32_e32 v81, v81
	v_exp_f32_e64 v97, v97
	v_pk_add_f32 v[250:251], v[66:67], v[68:69]
	v_pk_add_f32 v[252:253], v[82:83], v[84:85]
	v_pk_add_f32 v[250:251], v[250:251], v[70:71]
	v_pk_add_f32 v[252:253], v[252:253], v[86:87]
	v_pk_add_f32 v[250:251], v[250:251], v[72:73]
	v_pk_add_f32 v[252:253], v[252:253], v[88:89]
	v_pk_add_f32 v[250:251], v[250:251], v[74:75]
	v_pk_add_f32 v[252:253], v[252:253], v[90:91]
	v_pk_add_f32 v[250:251], v[250:251], v[76:77]
	v_pk_add_f32 v[252:253], v[252:253], v[92:93]
	v_pk_add_f32 v[250:251], v[250:251], v[78:79]
	v_pk_add_f32 v[252:253], v[252:253], v[94:95]
	v_pk_add_f32 v[250:251], v[250:251], v[80:81]
	v_pk_add_f32 v[252:253], v[252:253], v[96:97]
	v_pk_add_f32 v[250:251], v[250:251], v[252:253]
	v_add_f32_e32 v1, v250, v251
	v_cmp_lt_f32_e32 vcc, s26, v1
	s_cbranch_vccnz .Lat_rare_B2
.Lat_fast_B2:
	v_add_f32_e32 v227, v227, v1
	v_cvt_pk_bf16_f32 v66, v66, v67
	v_cvt_pk_bf16_f32 v67, v68, v69
	v_cvt_pk_bf16_f32 v68, v70, v71
	v_cvt_pk_bf16_f32 v69, v72, v73
	v_cvt_pk_bf16_f32 v74, v74, v75
	v_cvt_pk_bf16_f32 v75, v76, v77
	v_cvt_pk_bf16_f32 v76, v78, v79
	v_cvt_pk_bf16_f32 v77, v80, v81
	v_cvt_pk_bf16_f32 v82, v82, v83
	v_cvt_pk_bf16_f32 v83, v84, v85
	v_cvt_pk_bf16_f32 v84, v86, v87
	v_cvt_pk_bf16_f32 v85, v88, v89
	v_cvt_pk_bf16_f32 v90, v90, v91
	v_cvt_pk_bf16_f32 v91, v92, v93
	v_cvt_pk_bf16_f32 v92, v94, v95
	v_cvt_pk_bf16_f32 v93, v96, v97
	s_nop 0
	s_waitcnt lgkmcnt(9)
	v_mfma_f32_32x32x16_bf16 v[2:17], v[178:181], v[66:69], v[2:17]
	ds_read_b128 v[178:181], v225 offset:26848
	s_nop 0
	s_waitcnt lgkmcnt(8)
	v_mfma_f32_32x32x16_bf16 v[18:33], v[182:185], v[66:69], v[18:33]
	ds_read_b128 v[182:185], v225 offset:35552
	s_nop 0
	s_waitcnt lgkmcnt(7)
	v_mfma_f32_32x32x16_bf16 v[2:17], v[186:189], v[74:77], v[2:17]
	s_nop 0
	s_waitcnt lgkmcnt(5)
	v_mfma_f32_32x32x16_bf16 v[18:33], v[190:193], v[74:77], v[18:33]
	s_nop 0
	s_waitcnt lgkmcnt(3)
	v_mfma_f32_32x32x16_bf16 v[2:17], v[170:173], v[82:85], v[2:17]
	s_nop 0
	s_waitcnt lgkmcnt(2)
	v_mfma_f32_32x32x16_bf16 v[18:33], v[174:177], v[82:85], v[18:33]
	s_nop 0
	s_waitcnt lgkmcnt(1)
	v_mfma_f32_32x32x16_bf16 v[2:17], v[178:181], v[90:93], v[2:17]
	s_nop 0
	s_waitcnt lgkmcnt(0)
	v_mfma_f32_32x32x16_bf16 v[18:33], v[182:185], v[90:93], v[18:33]
	s_branch .Lat_nostage
.Lat_single:
	v_add_u32_e32 v1, s37, v222
	v_add_u32_e64 v225, s37, v223
	ds_read_b128 v[138:141], v1
	ds_read_b128 v[142:145], v1 offset:6656
	ds_read_b128 v[146:149], v1 offset:32
	ds_read_b128 v[150:153], v1 offset:6688
	ds_read_b128 v[154:157], v1 offset:64
	ds_read_b128 v[158:161], v1 offset:6720
	ds_read_b128 v[162:165], v1 offset:96
	ds_read_b128 v[166:169], v1 offset:6752
	s_waitcnt vmcnt(5)
	s_waitcnt lgkmcnt(7)
	v_mfma_f32_32x32x16_bf16 v[34:49], v[138:141], v[114:117], v[98:113]
	ds_read_b128 v[138:141], v1 offset:128
	s_nop 0
	s_waitcnt lgkmcnt(7)
	v_mfma_f32_32x32x16_bf16 v[50:65], v[142:145], v[114:117], v[98:113]
	ds_read_b128 v[142:145], v1 offset:6784
	s_nop 0
	s_waitcnt lgkmcnt(7)
	v_mfma_f32_32x32x16_bf16 v[34:49], v[146:149], v[118:121], v[34:49]
	ds_read_b128 v[146:149], v1 offset:160
	s_nop 0
	s_waitcnt lgkmcnt(7)
	v_mfma_f32_32x32x16_bf16 v[50:65], v[150:153], v[118:121], v[50:65]
	ds_read_b128 v[150:153], v1 offset:6816
	s_nop 0
	s_waitcnt lgkmcnt(7)
	v_mfma_f32_32x32x16_bf16 v[34:49], v[154:157], v[122:125], v[34:49]
	ds_read_b128 v[170:173], v225 offset:26624
	s_nop 0
	s_waitcnt lgkmcnt(7)
	v_mfma_f32_32x32x16_bf16 v[50:65], v[158:161], v[122:125], v[50:65]
	ds_read_b128 v[174:177], v225 offset:35328
	s_nop 0
	s_waitcnt lgkmcnt(7)
	v_mfma_f32_32x32x16_bf16 v[34:49], v[162:165], v[126:129], v[34:49]
	ds_read_b128 v[178:181], v225 offset:26656
	s_nop 0
	s_waitcnt lgkmcnt(7)
	v_mfma_f32_32x32x16_bf16 v[50:65], v[166:169], v[126:129], v[50:65]
	ds_read_b128 v[182:185], v225 offset:35360
	s_nop 0
	s_waitcnt lgkmcnt(7)
	v_mfma_f32_32x32x16_bf16 v[34:49], v[138:141], v[130:133], v[34:49]
	ds_read_b128 v[186:189], v225 offset:26688
	s_nop 0
	s_waitcnt lgkmcnt(7)
	v_mfma_f32_32x32x16_bf16 v[50:65], v[142:145], v[130:133], v[50:65]
	ds_read_b128 v[190:193], v225 offset:35392
	s_nop 0
	s_waitcnt lgkmcnt(7)
	v_mfma_f32_32x32x16_bf16 v[34:49], v[146:149], v[134:137], v[34:49]
	s_nop 0
	s_waitcnt lgkmcnt(6)
	v_mfma_f32_32x32x16_bf16 v[50:65], v[150:153], v[134:137], v[50:65]
	s_mov_b32 s41, 0
	s_cmp_lg_u32 s7, 0
	s_cbranch_scc1 .Lat_first_A1
; #define LAS __attribute__((address_space(3)))
; __device__ __forceinline__ void attn_phase(LAS unsigned char* lds, const bf16_t* __restrict__ Q, const bf16_t* __restrict__ KN, const bf16_t* __restrict__ KR,
;                                            const bf16_t* __restrict__ VT, bf16_t* AO, int vcu, int G, int tid, int lane, int wave) {
;     ...
;                     attn_ldv(vf, vA);
;                     __builtin_amdgcn_sched_barrier(0);
;                     attn_softmax(a0, a1, pa, o0, o1, m_run, l_run);
;                     __builtin_amdgcn_sched_barrier(0);
;                     attn_pv(vf, pa, o0, o1);
;                 } else { PREFETCH_NEXT(); }
;                 if (more) { LAS unsigned char* nb = lds + ((t + 1) & 1) * BUF;
;                     *(LAS u32x4*)(nb + kdst) = gk0; *(LAS u32x4*)(nb + kdst + 64 * KP * 2) = gk1; *(LAS u32x4*)(nb + rdst) = gr; *(LAS u32x4*)(nb + vdst) = gv0; *(LAS u32x4*)(nb + vdst + 128) = gv1; }
.Lat_exp_A1:
	s_nop 6
	v_exp_f32_e32 v34, v34
	s_nop 0
	v_exp_f32_e32 v50, v50
	v_exp_f32_e32 v35, v35
	v_exp_f32_e32 v51, v51
	v_exp_f32_e32 v36, v36
	v_exp_f32_e32 v52, v52
	v_exp_f32_e32 v37, v37
	v_exp_f32_e32 v53, v53
	v_exp_f32_e32 v38, v38
	v_exp_f32_e32 v54, v54
	v_exp_f32_e32 v39, v39
	v_exp_f32_e32 v55, v55
	v_exp_f32_e32 v40, v40
	v_exp_f32_e32 v56, v56
	v_exp_f32_e32 v41, v41
	v_exp_f32_e32 v57, v57
	v_exp_f32_e32 v42, v42
	v_exp_f32_e32 v58, v58
	v_exp_f32_e32 v43, v43
	v_exp_f32_e32 v59, v59
	v_exp_f32_e32 v44, v44
	v_exp_f32_e32 v60, v60
	v_exp_f32_e32 v45, v45
	v_exp_f32_e32 v61, v61
	v_exp_f32_e32 v46, v46
	v_exp_f32_e32 v62, v62
	v_exp_f32_e32 v47, v47
	v_exp_f32_e32 v63, v63
	v_exp_f32_e32 v48, v48
	v_exp_f32_e32 v64, v64
	v_exp_f32_e32 v49, v49
	v_exp_f32_e64 v65, v65
	v_pk_add_f32 v[250:251], v[34:35], v[36:37]
	v_pk_add_f32 v[252:253], v[50:51], v[52:53]
	v_pk_add_f32 v[250:251], v[250:251], v[38:39]
	v_pk_add_f32 v[252:253], v[252:253], v[54:55]
	v_pk_add_f32 v[250:251], v[250:251], v[40:41]
	v_pk_add_f32 v[252:253], v[252:253], v[56:57]
	v_pk_add_f32 v[250:251], v[250:251], v[42:43]
	v_pk_add_f32 v[252:253], v[252:253], v[58:59]
	v_pk_add_f32 v[250:251], v[250:251], v[44:45]
	v_pk_add_f32 v[252:253], v[252:253], v[60:61]
	v_pk_add_f32 v[250:251], v[250:251], v[46:47]
	v_pk_add_f32 v[252:253], v[252:253], v[62:63]
	v_pk_add_f32 v[250:251], v[250:251], v[48:49]
	v_pk_add_f32 v[252:253], v[252:253], v[64:65]
	v_pk_add_f32 v[250:251], v[250:251], v[252:253]
	v_add_f32_e32 v1, v250, v251
	v_cmp_lt_f32_e32 vcc, s26, v1
	s_cbranch_vccnz .Lat_rare_A1
.Lat_fast_A1:
	v_add_f32_e32 v227, v227, v1
	v_cvt_pk_bf16_f32 v34, v34, v35
	v_cvt_pk_bf16_f32 v35, v36, v37
	v_cvt_pk_bf16_f32 v36, v38, v39
	v_cvt_pk_bf16_f32 v37, v40, v41
	v_cvt_pk_bf16_f32 v42, v42, v43
	v_cvt_pk_bf16_f32 v43, v44, v45
	v_cvt_pk_bf16_f32 v44, v46, v47
	v_cvt_pk_bf16_f32 v45, v48, v49
	v_cvt_pk_bf16_f32 v50, v50, v51
	v_cvt_pk_bf16_f32 v51, v52, v53
	v_cvt_pk_bf16_f32 v52, v54, v55
	v_cvt_pk_bf16_f32 v53, v56, v57
	v_cvt_pk_bf16_f32 v58, v58, v59
	v_cvt_pk_bf16_f32 v59, v60, v61
	v_cvt_pk_bf16_f32 v60, v62, v63
	v_cvt_pk_bf16_f32 v61, v64, v65
	s_nop 0
	s_waitcnt lgkmcnt(5)
	v_mfma_f32_32x32x16_bf16 v[2:17], v[170:173], v[34:37], v[2:17]
	ds_read_b128 v[170:173], v225 offset:26720
	s_nop 0
	s_waitcnt lgkmcnt(5)
	v_mfma_f32_32x32x16_bf16 v[18:33], v[174:177], v[34:37], v[18:33]
	ds_read_b128 v[174:177], v225 offset:35424
	s_nop 0
	s_waitcnt lgkmcnt(5)
	v_mfma_f32_32x32x16_bf16 v[2:17], v[178:181], v[42:45], v[2:17]
	s_nop 0
	s_waitcnt lgkmcnt(4)
	v_mfma_f32_32x32x16_bf16 v[18:33], v[182:185], v[42:45], v[18:33]
	s_nop 0
	s_waitcnt lgkmcnt(3)
	v_mfma_f32_32x32x16_bf16 v[2:17], v[186:189], v[50:53], v[2:17]
	s_nop 0
	s_waitcnt lgkmcnt(2)
	v_mfma_f32_32x32x16_bf16 v[18:33], v[190:193], v[50:53], v[18:33]
	s_nop 0
	s_waitcnt lgkmcnt(1)
	v_mfma_f32_32x32x16_bf16 v[2:17], v[170:173], v[58:61], v[2:17]
	s_nop 0
	s_waitcnt lgkmcnt(0)
	v_mfma_f32_32x32x16_bf16 v[18:33], v[174:177], v[58:61], v[18:33]
.Lat_tail:
	s_cmp_lt_u32 s39, s36
	s_cbranch_scc0 .Lat_nostage
	s_waitcnt vmcnt(0)
	v_add_u32_e32 v1, s38, v219
	ds_write_b128 v1, v[228:231]
	ds_write_b128 v1, v[232:235] offset:13312
	v_add_u32_e64 v1, s38, v220
	ds_write_b128 v1, v[236:239]
	v_add_u32_e64 v1, s38, v221
	ds_write_b128 v1, v[240:243] offset:26624
	ds_write_b128 v1, v[244:247] offset:26752

; template <class Epi, class Sched, bool ALIGN_EPI = false, bool SP2 = false>
; __device__ __forceinline__ void gemm_phase(PG8_LAS unsigned char* lds, const Gemm g, const Sched& S, const Epi& E) {
;     ...
;         const bool has_next = S.next(ui + 1, nxt);
;         const char* nA = has_next ? (const char*)g.A + (size_t)nxt.pm * tstep : cA; const char* nB = has_next ? (const char*)g.Bt + (size_t)nxt.pn * tstep : cB;
;     ...
; #pragma unroll
;         for (int a = 0; a < 2; ++a)
; #pragma unroll
;             for (int b = 0; b < 2; ++b)
; #pragma unroll
;                 for (int m = 0; m < 4; ++m)
; #pragma unroll
;                     for (int n = 0; n < 2; ++n) acc[a][b][m][n] = (f32x4){0.f, 0.f, 0.f, 0.f};
;         cur = nxt; cA = nA; cB = nB; ++ui;
.LBB0_616:
	s_ashr_i32 s43, s42, 31
	s_lshl_b64 s[44:45], s[42:43], 19
	s_add_u32 s44, s18, s44
	s_addc_u32 s45, s19, s45
	s_and_b64 s[46:47], s[6:7], exec
	s_cselect_b32 s43, s45, s51
	s_cselect_b32 s68, s44, s50
	s_ashr_i32 s41, s40, 31
	s_lshl_b64 s[46:47], s[40:41], 19
	s_add_u32 s46, s31, s46
	s_addc_u32 s47, s33, s47
	s_and_b64 s[54:55], s[6:7], exec
	s_cselect_b32 s41, s47, s53
	s_cselect_b32 s69, s46, s52
	s_add_u32 s50, s50, 0x40080
	s_addc_u32 s51, s51, 0
	s_add_u32 s70, s52, 0x100
	v_mov_b32_e32 v0, 0
	s_addc_u32 s71, s53, 0
	s_mov_b32 s72, -2
	v_mov_b32_e32 v1, v0
	v_mov_b32_e32 v2, v0
	v_mov_b32_e32 v3, v0
	v_mov_b32_e32 v4, v0
	v_mov_b32_e32 v5, v0
	v_mov_b32_e32 v6, v0
	v_mov_b32_e32 v7, v0
	v_mov_b32_e32 v8, v0
	v_mov_b32_e32 v9, v0
	v_mov_b32_e32 v10, v0
	v_mov_b32_e32 v11, v0
	v_mov_b32_e32 v16, v0
	v_mov_b32_e32 v17, v0
	v_mov_b32_e32 v18, v0
	v_mov_b32_e32 v19, v0
	v_mov_b32_e32 v24, v0
	v_mov_b32_e32 v25, v0
	v_mov_b32_e32 v26, v0
	v_mov_b32_e32 v27, v0
	v_mov_b32_e32 v32, v0
	v_mov_b32_e32 v33, v0
	v_mov_b32_e32 v34, v0
	v_mov_b32_e32 v35, v0
	v_mov_b32_e32 v40, v0
	v_mov_b32_e32 v41, v0
	v_mov_b32_e32 v42, v0
	v_mov_b32_e32 v43, v0
	v_mov_b32_e32 v48, v0
	v_mov_b32_e32 v49, v0
	v_mov_b32_e32 v50, v0
	v_mov_b32_e32 v51, v0
	v_mov_b32_e32 v12, v0
	v_mov_b32_e32 v13, v0
	v_mov_b32_e32 v14, v0
	v_mov_b32_e32 v15, v0
	v_mov_b32_e32 v20, v0
	v_mov_b32_e32 v21, v0
	v_mov_b32_e32 v22, v0
	v_mov_b32_e32 v23, v0
	v_mov_b32_e32 v28, v0
	v_mov_b32_e32 v29, v0
	v_mov_b32_e32 v30, v0
	v_mov_b32_e32 v31, v0
	v_mov_b32_e32 v36, v0
	v_mov_b32_e32 v37, v0
	v_mov_b32_e32 v38, v0
	v_mov_b32_e32 v39, v0
	v_mov_b32_e32 v44, v0
	v_mov_b32_e32 v45, v0
	v_mov_b32_e32 v46, v0
	v_mov_b32_e32 v47, v0
	v_mov_b32_e32 v52, v0
	v_mov_b32_e32 v53, v0
	v_mov_b32_e32 v54, v0
	v_mov_b32_e32 v55, v0
	v_mov_b32_e32 v56, v0
	v_mov_b32_e32 v57, v0
	v_mov_b32_e32 v58, v0
	v_mov_b32_e32 v59, v0
	v_mov_b32_e32 v60, v0
	v_mov_b32_e32 v61, v0
	v_mov_b32_e32 v62, v0
	v_mov_b32_e32 v63, v0
	v_mov_b32_e32 v64, v0
	v_mov_b32_e32 v65, v0
	v_mov_b32_e32 v66, v0
	v_mov_b32_e32 v67, v0
	v_mov_b32_e32 v68, v0
	v_mov_b32_e32 v69, v0
	v_mov_b32_e32 v70, v0
	v_mov_b32_e32 v71, v0
	v_mov_b32_e32 v72, v0
	v_mov_b32_e32 v73, v0
	v_mov_b32_e32 v74, v0
	v_mov_b32_e32 v75, v0
	v_mov_b32_e32 v80, v0
	v_mov_b32_e32 v81, v0
	v_mov_b32_e32 v82, v0
	v_mov_b32_e32 v83, v0
	v_mov_b32_e32 v88, v0
	v_mov_b32_e32 v89, v0
	v_mov_b32_e32 v90, v0
	v_mov_b32_e32 v91, v0
	v_mov_b32_e32 v96, v0
	v_mov_b32_e32 v97, v0
	v_mov_b32_e32 v98, v0
	v_mov_b32_e32 v99, v0
	v_mov_b32_e32 v104, v0
	v_mov_b32_e32 v105, v0
	v_mov_b32_e32 v106, v0
	v_mov_b32_e32 v107, v0
	v_mov_b32_e32 v112, v0
	v_mov_b32_e32 v113, v0
	v_mov_b32_e32 v114, v0
	v_mov_b32_e32 v115, v0
	v_mov_b32_e32 v76, v0
	v_mov_b32_e32 v77, v0
	v_mov_b32_e32 v78, v0
	v_mov_b32_e32 v79, v0
	v_mov_b32_e32 v84, v0
	v_mov_b32_e32 v85, v0
	v_mov_b32_e32 v86, v0
	v_mov_b32_e32 v87, v0
	v_mov_b32_e32 v92, v0
	v_mov_b32_e32 v93, v0
	v_mov_b32_e32 v94, v0
	v_mov_b32_e32 v95, v0
	v_mov_b32_e32 v100, v0
	v_mov_b32_e32 v101, v0
	v_mov_b32_e32 v102, v0
	v_mov_b32_e32 v103, v0
	v_mov_b32_e32 v108, v0
	v_mov_b32_e32 v109, v0
	v_mov_b32_e32 v110, v0
	v_mov_b32_e32 v111, v0
	v_mov_b32_e32 v116, v0
	v_mov_b32_e32 v117, v0
	v_mov_b32_e32 v118, v0
	v_mov_b32_e32 v119, v0
	v_mov_b32_e32 v120, v0
	v_mov_b32_e32 v121, v0
	v_mov_b32_e32 v122, v0
	v_mov_b32_e32 v123, v0
	v_mov_b32_e32 v124, v0
	v_mov_b32_e32 v125, v0
	v_mov_b32_e32 v126, v0
	v_mov_b32_e32 v127, v0
	s_nop 0
	s_nop 0
	s_nop 0
	s_nop 0
	s_nop 0
	s_nop 0
	s_nop 0
	s_nop 0
	s_nop 0
	s_nop 0
	s_nop 0
	s_nop 0

;     __device__ __forceinline__ void operator()(const f32x4 (&acc)[2][2][4][2], const Unit& u, int wr, int wc, int fr, int fq) const {
;     ...
;         if (fq == 3) {
; #pragma unroll
;             for (int ai = 0; ai < 2; ++ai)
; #pragma unroll
;                 for (int bj = 0; bj < 2; ++bj)
; #pragma unroll
;                     for (int n = 0; n < 2; ++n) { PG8_LAS float* hp = halo + (((((ai * 2 + wr) * 4 + wc) * 2 + bj) * 2 + n) * 32) + fr; hp[0] = acc[ai][bj][3][n][2]; hp[16] = acc[ai][bj][3][n][3]; }
;         }
;         asm volatile("s_waitcnt lgkmcnt(0)" ::: "memory"); __builtin_amdgcn_s_barrier(); asm volatile("" ::: "memory");
;         const int src = ((lane - 16) & 63) * 4;
; #pragma unroll
;         for (int ai = 0; ai < 2; ++ai) {
;             const int blk = 2 * ai + wr;
; #pragma unroll
;             for (int m = 0; m < 4; ++m) {
;                 float o[2][4];
; #pragma unroll
;                 for (int n = 0; n < 2; ++n) {
;                     const f32x4 Xa = acc[ai][0][m][n], Xb = acc[ai][1][m][n];
;                     float da2, da3, db2, db3;
;                     if (m > 0) { const bool t = (fq == 3); da2 = t ? acc[ai][0][m > 0 ? m - 1 : 0][n][2] : Xa[2]; da3 = t ? acc[ai][0][m > 0 ? m - 1 : 0][n][3] : Xa[3];
;                                  db2 = t ? acc[ai][1][m > 0 ? m - 1 : 0][n][2] : Xb[2]; db3 = t ? acc[ai][1][m > 0 ? m - 1 : 0][n][3] : Xb[3]; }
;                     else { da2 = Xa[2]; da3 = Xa[3]; db2 = Xb[2]; db3 = Xb[3]; }
;                     float Ha2 = __builtin_bit_cast(float, __builtin_amdgcn_ds_bpermute(src, __builtin_bit_cast(int, da2)));
;                     float Ha3 = __builtin_bit_cast(float, __builtin_amdgcn_ds_bpermute(src, __builtin_bit_cast(int, da3)));
;                     float Hb2 = __builtin_bit_cast(float, __builtin_amdgcn_ds_bpermute(src, __builtin_bit_cast(int, db2)));
;                     float Hb3 = __builtin_bit_cast(float, __builtin_amdgcn_ds_bpermute(src, __builtin_bit_cast(int, db3)));
;                     if (m == 0) {
;                         float h2a = 0.f, h3a = 0.f, h2b = 0.f, h3b = 0.f;
;                         if (blk > 0) { const PG8_LAS float* hp = halo + ((((blk - 1) * 4 + wc) * 2 + 0) * 2 + n) * 32 + fr; h2a = hp[0]; h3a = hp[16]; h2b = hp[64]; h3b = hp[80]; }
;                         if (fq == 0) { Ha2 = h2a; Ha3 = h3a; Hb2 = h2b; Hb3 = h3b; }
;                     }
.LBB0_889:
	v_readfirstlane_b32 s19, v195
	v_and_b32_e32 v190, 15, v195
	v_bfe_u32 v191, v195, 4, 2
	s_lshr_b32 s19, s19, 6
	s_and_b32 s24, s19, 3
	s_lshr_b32 s25, s19, 2
	v_lshrrev_b32_e64 v192, 2, v237
	s_lshl_b32 s27, s25, 6
	v_lshl_add_u32 v193, v191, 2, s27
	v_mul_u32_u24_e32 v193, 0x1600, v193
	v_lshl_add_u32 v157, v192, 1, v193
	v_add_u32_e32 v158, 48, v195
	v_and_b32_e32 v158, 63, v158
	v_lshlrev_b32_e32 v158, 2, v158
	s_lshl_b32 s27, s25, 11
	s_lshl_b32 s17, s24, 9
	s_add_i32 s27, s27, s17
	s_add_i32 s27, s27, 0x20400
	v_lshl_add_u32 v159, v190, 2, s27
	v_add_u32_e32 v160, 0xfffff800, v159
	v_mov_b32_e32 v162, 1.0
	v_mov_b32_e64 v163, 1.0
	s_and_saveexec_b64 s[16:17], s[6:7]
	ds_write_b32 v159, v70
	ds_write_b32 v159, v71 offset:64
	ds_write_b32 v159, v78 offset:128
	ds_write_b32 v159, v79 offset:192
	ds_write_b32 v159, v66 offset:256
	ds_write_b32 v159, v67 offset:320
	ds_write_b32 v159, v74 offset:384
	ds_write_b32 v159, v75 offset:448
	ds_write_b32 v159, v2 offset:4096
	ds_write_b32 v159, v3 offset:4160
	ds_write_b32 v159, v14 offset:4224
	ds_write_b32 v159, v15 offset:4288
	ds_write_b32 v159, v6 offset:4352
	ds_write_b32 v159, v7 offset:4416
	s_nop 0
	s_waitcnt lgkmcnt(13)
	ds_write_b32 v159, v10 offset:4480
	s_nop 0
	s_waitcnt lgkmcnt(13)
	ds_write_b32 v159, v11 offset:4544
	s_nop 0
	s_or_b64 exec, exec, s[16:17]
	s_waitcnt lgkmcnt(0)
	s_barrier
	s_cmp_eq_u32 s25, 0
	s_cbranch_scc1 .Lp8_nohalo
	ds_read_b32 v228, v160
	ds_read_b32 v229, v160 offset:64
	ds_read_b32 v230, v160 offset:256
	ds_read_b32 v231, v160 offset:320
	ds_read_b32 v232, v160 offset:128
	ds_read_b32 v233, v160 offset:192
	ds_read_b32 v234, v160 offset:384
	ds_read_b32 v235, v160 offset:448
	s_branch .Lp8_halo_done
.Lp8_nohalo:
	v_mov_b32_e32 v228, 0
	v_mov_b32_e32 v229, 0
	v_mov_b32_e32 v230, 0
	v_mov_b32_e32 v231, 0
	v_mov_b32_e32 v232, 0
	v_mov_b32_e32 v233, 0
	v_mov_b32_e32 v234, 0
	v_mov_b32_e64 v235, 0
.Lp8_halo_done:
	ds_bpermute_b32 v196, v158, v126
	ds_bpermute_b32 v197, v158, v127
	ds_bpermute_b32 v198, v158, v122
	ds_bpermute_b32 v199, v158, v123
	ds_bpermute_b32 v200, v158, v118
	ds_bpermute_b32 v201, v158, v119
	s_nop 0
	s_waitcnt lgkmcnt(13)
	ds_bpermute_b32 v202, v158, v114
	s_nop 0
	s_waitcnt lgkmcnt(13)
	ds_bpermute_b32 v203, v158, v115
	v_mul_f32_e32 v238, 0xbfb8aa3b, v238
	v_mul_f32_e32 v239, 0xbfb8aa3b, v239
	v_mul_f32_e32 v244, 0xbf317218, v244
	v_mul_f32_e32 v245, 0xbf317218, v245
	v_mul_f32_e32 v240, 0xbfb8aa3b, v240
	v_mul_f32_e32 v241, 0xbfb8aa3b, v241
	v_mul_f32_e32 v246, 0xbf317218, v246
	v_mul_f32_e32 v247, 0xbf317218, v247
	v_mul_f32_e32 v242, 0xbfb8aa3b, v242
	v_mul_f32_e32 v243, 0xbfb8aa3b, v243
	v_mul_f32_e32 v248, 0xbf317218, v248
	v_mul_f32_e32 v249, 0xbf317218, v249
	v_mul_f32_e32 v250, 0xbfb8aa3b, v250
	v_mul_f32_e32 v251, 0xbfb8aa3b, v251
	v_mul_f32_e32 v252, 0xbf317218, v252
	v_mul_f32_e32 v253, 0xbf317218, v253
	s_mul_i32 s26, s74, 0x16000
	s_nop 0
	s_add_u32 s26, s87, s26
	s_addc_u32 s27, s88, 0
	s_cmp_eq_u32 s25, 0
	s_cbranch_scc0 .Lp8_side_hi
	s_and_saveexec_b64 s[16:17], s[8:9]
	global_store_dword v237, v124, s[26:27]
	global_store_dword v237, v116, s[26:27] offset:4
	s_add_u32 s26, s26, 0x2c00
	s_nop 0
	s_addc_u32 s27, s27, 0
	global_store_dword v237, v120, s[26:27]
	global_store_dword v237, v112, s[26:27] offset:4
	s_add_u32 s26, s26, 0x2c00
	s_nop 0
	s_addc_u32 s27, s27, 0
	global_store_dword v237, v125, s[26:27]
	global_store_dword v237, v117, s[26:27] offset:4
	s_add_u32 s26, s26, 0x2c00
	s_nop 0
	s_addc_u32 s27, s27, 0
	global_store_dword v237, v121, s[26:27]
	global_store_dword v237, v113, s[26:27] offset:4
	s_add_u32 s26, s26, 0x2c00
	s_nop 0
	s_addc_u32 s27, s27, 0
	s_or_b64 exec, exec, s[16:17]
	s_branch .Lp8_side_done
.Lp8_side_hi:
	s_add_u32 s26, s26, 0xb000
	s_addc_u32 s27, s27, 0
	s_and_saveexec_b64 s[16:17], s[6:7]
	global_store_dword v237, v2, s[26:27]
	global_store_dword v237, v14, s[26:27] offset:4
	s_add_u32 s26, s26, 0x2c00
	s_nop 0
	s_addc_u32 s27, s27, 0
	global_store_dword v237, v6, s[26:27]
	global_store_dword v237, v10, s[26:27] offset:4
	s_add_u32 s26, s26, 0x2c00
	s_nop 0
	s_addc_u32 s27, s27, 0
	global_store_dword v237, v3, s[26:27]
	global_store_dword v237, v15, s[26:27] offset:4
	s_add_u32 s26, s26, 0x2c00
	s_nop 0
	s_addc_u32 s27, s27, 0
	global_store_dword v237, v7, s[26:27]
	global_store_dword v237, v11, s[26:27] offset:4
	s_add_u32 s26, s26, 0x2c00
	s_addc_u32 s27, s27, 0
	s_or_b64 exec, exec, s[16:17]
;     __device__ __forceinline__ void operator()(const f32x4 (&acc)[2][2][4][2], const Unit& u, int wr, int wc, int fr, int fq) const {
;     ...
;                 for (int n = 0; n < 2; ++n) {
;                     const f32x4 Xa = acc[ai][0][m][n], Xb = acc[ai][1][m][n];
;                     float da2, da3, db2, db3;
;                     if (m > 0) { const bool t = (fq == 3); da2 = t ? acc[ai][0][m > 0 ? m - 1 : 0][n][2] : Xa[2]; da3 = t ? acc[ai][0][m > 0 ? m - 1 : 0][n][3] : Xa[3];
;                                  db2 = t ? acc[ai][1][m > 0 ? m - 1 : 0][n][2] : Xb[2]; db3 = t ? acc[ai][1][m > 0 ? m - 1 : 0][n][3] : Xb[3]; }
;                     else { da2 = Xa[2]; da3 = Xa[3]; db2 = Xb[2]; db3 = Xb[3]; }
;                     float Ha2 = __builtin_bit_cast(float, __builtin_amdgcn_ds_bpermute(src, __builtin_bit_cast(int, da2)));
;                     float Ha3 = __builtin_bit_cast(float, __builtin_amdgcn_ds_bpermute(src, __builtin_bit_cast(int, da3)));
;                     float Hb2 = __builtin_bit_cast(float, __builtin_amdgcn_ds_bpermute(src, __builtin_bit_cast(int, db2)));
;                     float Hb3 = __builtin_bit_cast(float, __builtin_amdgcn_ds_bpermute(src, __builtin_bit_cast(int, db3)));
;                     if (m == 0) {
;                         float h2a = 0.f, h3a = 0.f, h2b = 0.f, h3b = 0.f;
;                         if (blk > 0) { const PG8_LAS float* hp = halo + ((((blk - 1) * 4 + wc) * 2 + 0) * 2 + n) * 32 + fr; h2a = hp[0]; h3a = hp[16]; h2b = hp[64]; h3b = hp[80]; }
;                         if (fq == 0) { Ha2 = h2a; Ha3 = h3a; Hb2 = h2b; Hb3 = h3b; }
;                     }
;                     const f32x2_t W0 = {wa[n][0], wb[n][0]}, W1 = {wa[n][1], wb[n][1]}, W2 = {wa[n][2], wb[n][2]}, B2 = {ba[n], bb[n]};
;                     const f32x2_t H2 = {Ha2, Hb2}, H3 = {Ha3, Hb3}, X0 = {Xa[0], Xb[0]}, X1 = {Xa[1], Xb[1]}, X2 = {Xa[2], Xb[2]}, X3 = {Xa[3], Xb[3]};
;                     const f32x2_t y0 = B2 + W0 * H2 + W1 * H3 + W2 * X0, y1 = B2 + W0 * H3 + W1 * X0 + W2 * X1, y2 = B2 + W0 * X0 + W1 * X1 + W2 * X2, y3 = B2 + W0 * X1 + W1 * X2 + W2 * X3;
;                     const float ya0 = y0[0], yb0 = y0[1], ya1 = y1[0], yb1 = y1[1], ya2 = y2[0], yb2 = y2[1], ya3 = y3[0], yb3 = y3[1];
;                     o[n][0] = silu_f(ya0) * yb0; o[n][1] = silu_f(ya1) * yb1; o[n][2] = silu_f(ya2) * yb2; o[n][3] = silu_f(ya3) * yb3;
.Lp8_side_done:
	s_mul_i32 s76, s74, 0x160000
	s_nop 0
	s_add_u32 s76, s40, s76
	s_addc_u32 s77, s41, 0
	s_waitcnt lgkmcnt(13)
	ds_bpermute_b32 v204, v158, v110
	s_nop 0
	s_waitcnt lgkmcnt(13)
	ds_bpermute_b32 v205, v158, v111
	s_nop 0
	s_waitcnt lgkmcnt(13)
	ds_bpermute_b32 v206, v158, v106
	s_nop 0
	s_waitcnt lgkmcnt(13)
	ds_bpermute_b32 v207, v158, v107
	s_nop 0
	s_waitcnt lgkmcnt(13)
	ds_bpermute_b32 v208, v158, v102
	s_nop 0
	s_waitcnt lgkmcnt(13)
	ds_bpermute_b32 v209, v158, v103
	s_nop 0
	s_waitcnt lgkmcnt(13)
	ds_bpermute_b32 v210, v158, v98
	s_nop 0
	s_waitcnt lgkmcnt(13)
	ds_bpermute_b32 v211, v158, v99
	s_nop 0
	s_waitcnt lgkmcnt(12)
	v_cndmask_b32_e64 v140, v196, v228, s[8:9]
	v_cndmask_b32_e64 v141, v197, v229, s[8:9]
	v_cndmask_b32_e64 v142, v198, v230, s[8:9]
	v_cndmask_b32_e64 v143, v199, v231, s[8:9]
	v_pk_fma_f32 v[164:165], v[238:239], v[140:141], v[250:251] op_sel_hi:[0,1,0]
	v_pk_fma_f32 v[168:169], v[244:245], v[142:143], v[252:253] op_sel_hi:[0,1,0]
	v_pk_fma_f32 v[166:167], v[238:239], v[124:125], v[250:251] op_sel_hi:[0,1,0]
	v_pk_fma_f32 v[170:171], v[244:245], v[120:121], v[252:253] op_sel_hi:[0,1,0]
	v_pk_fma_f32 v[164:165], v[242:243], v[124:125], v[164:165] op_sel_hi:[0,1,1]
	v_pk_fma_f32 v[168:169], v[248:249], v[120:121], v[168:169] op_sel_hi:[0,1,1]
	v_pk_fma_f32 v[166:167], v[242:243], v[126:127], v[166:167] op_sel_hi:[0,1,1]
	v_pk_fma_f32 v[170:171], v[248:249], v[122:123], v[170:171] op_sel_hi:[0,1,1]
	v_fmac_f32_e32 v164, v240, v141
	v_fmac_f32_e32 v168, v246, v143
	v_fmac_f32_e32 v165, v240, v124
	v_fmac_f32_e32 v169, v246, v120
	v_fmac_f32_e32 v166, v240, v125
	v_fmac_f32_e32 v170, v246, v121
	v_fmac_f32_e32 v167, v240, v126
	v_fmac_f32_e32 v171, v246, v122
	v_exp_f32_e32 v144, v164
	v_exp_f32_e32 v145, v165
	v_exp_f32_e32 v146, v166
	v_exp_f32_e32 v147, v167
	v_pk_mul_f32 v[164:165], v[164:165], v[168:169]
	v_pk_mul_f32 v[166:167], v[166:167], v[170:171]
	v_pk_add_f32 v[144:145], v[144:145], v[162:163]
	v_pk_add_f32 v[146:147], v[146:147], v[162:163]
	v_rcp_f32_e32 v144, v144
	v_rcp_f32_e32 v145, v145
	v_rcp_f32_e32 v146, v146
	v_rcp_f32_e64 v147, v147
	s_waitcnt lgkmcnt(8)
	v_cndmask_b32_e64 v140, v200, v232, s[8:9]
	v_cndmask_b32_e64 v141, v201, v233, s[8:9]
	v_cndmask_b32_e64 v142, v202, v234, s[8:9]
	v_cndmask_b32_e64 v143, v203, v235, s[8:9]
	v_pk_fma_f32 v[182:183], v[238:239], v[140:141], v[250:251] op_sel:[1,0,1] op_sel_hi:[1,1,1]
	v_pk_fma_f32 v[186:187], v[244:245], v[142:143], v[252:253] op_sel:[1,0,1] op_sel_hi:[1,1,1]
	v_pk_fma_f32 v[184:185], v[238:239], v[116:117], v[250:251] op_sel:[1,0,1] op_sel_hi:[1,1,1]
	v_pk_fma_f32 v[188:189], v[244:245], v[112:113], v[252:253] op_sel:[1,0,1] op_sel_hi:[1,1,1]
	v_pk_fma_f32 v[182:183], v[242:243], v[116:117], v[182:183] op_sel:[1,0,0] op_sel_hi:[1,1,1]
	v_pk_fma_f32 v[186:187], v[248:249], v[112:113], v[186:187] op_sel:[1,0,0] op_sel_hi:[1,1,1]
	v_pk_fma_f32 v[184:185], v[242:243], v[118:119], v[184:185] op_sel:[1,0,0] op_sel_hi:[1,1,1]
	v_pk_fma_f32 v[188:189], v[248:249], v[114:115], v[188:189] op_sel:[1,0,0] op_sel_hi:[1,1,1]
	v_fmac_f32_e32 v182, v241, v141
	v_fmac_f32_e32 v186, v247, v143
	v_fmac_f32_e32 v183, v241, v116
	v_fmac_f32_e32 v187, v247, v112
	v_fmac_f32_e32 v184, v241, v117
	v_fmac_f32_e32 v188, v247, v113
	v_fmac_f32_e32 v185, v241, v118
	v_fmac_f32_e32 v189, v247, v114
	v_exp_f32_e32 v148, v182
	v_exp_f32_e32 v149, v183
	v_exp_f32_e32 v150, v184
	v_exp_f32_e32 v151, v185
	v_pk_mul_f32 v[182:183], v[182:183], v[186:187]
	v_pk_mul_f32 v[184:185], v[184:185], v[188:189]
	v_pk_add_f32 v[148:149], v[148:149], v[162:163]
	v_pk_add_f32 v[150:151], v[150:151], v[162:163]
	v_rcp_f32_e32 v148, v148
	v_rcp_f32_e32 v149, v149
	v_rcp_f32_e32 v150, v150
	v_rcp_f32_e32 v151, v151
	v_pk_mul_f32 v[164:165], v[164:165], v[144:145]
	v_pk_mul_f32 v[166:167], v[166:167], v[146:147]
	v_pk_mul_f32 v[182:183], v[182:183], v[148:149]
	v_pk_mul_f32 v[184:185], v[184:185], v[150:151]
	v_cvt_pk_bf16_f32 v152, v164, v182
	v_cvt_pk_bf16_f32 v153, v165, v183
	v_cvt_pk_bf16_f32 v154, v166, v184
	v_cvt_pk_bf16_f32 v155, v167, v185
	global_store_dword v157, v152, s[76:77]
	s_add_u32 s76, s76, 0x1600
	s_nop 0
	s_addc_u32 s77, s77, 0
	global_store_dword v157, v153, s[76:77]
	s_add_u32 s76, s76, 0x1600
	s_nop 0
	s_addc_u32 s77, s77, 0
	global_store_dword v157, v154, s[76:77]
	s_add_u32 s76, s76, 0x1600
	s_nop 0
	s_addc_u32 s77, s77, 0
	global_store_dword v157, v155, s[76:77]
	s_add_u32 s76, s76, 0x11e00
	s_nop 0
	s_addc_u32 s77, s77, 0
	ds_bpermute_b32 v212, v158, v94
	ds_bpermute_b32 v213, v158, v95
	ds_bpermute_b32 v214, v158, v90
	ds_bpermute_b32 v215, v158, v91
	ds_bpermute_b32 v216, v158, v86
	ds_bpermute_b32 v217, v158, v87
	s_nop 0
	s_waitcnt lgkmcnt(13)
	ds_bpermute_b32 v218, v158, v82
	s_nop 0
	s_waitcnt lgkmcnt(13)
	ds_bpermute_b32 v219, v158, v83
	s_nop 0
	s_waitcnt lgkmcnt(13)
	ds_read_b32 v228, v159 offset:2048
	s_nop 0
	s_waitcnt lgkmcnt(13)
	ds_read_b32 v229, v159 offset:2112
	s_nop 0
	s_waitcnt lgkmcnt(13)
	ds_read_b32 v230, v159 offset:2304
	s_nop 0
	s_waitcnt lgkmcnt(13)
	ds_read_b32 v231, v159 offset:2368
	s_nop 0
	s_waitcnt lgkmcnt(13)
	ds_read_b32 v232, v159 offset:2176
	s_nop 0
	s_waitcnt lgkmcnt(13)
	ds_read_b32 v233, v159 offset:2240
	s_nop 0
	s_waitcnt lgkmcnt(13)
	ds_read_b32 v234, v159 offset:2432
	s_nop 0
	s_waitcnt lgkmcnt(13)
;     __device__ __forceinline__ void operator()(const f32x4 (&acc)[2][2][4][2], const Unit& u, int wr, int wc, int fr, int fq) const {
;     ...
;                 for (int n = 0; n < 2; ++n) {
;                     const f32x4 Xa = acc[ai][0][m][n], Xb = acc[ai][1][m][n];
;                     float da2, da3, db2, db3;
;                     if (m > 0) { const bool t = (fq == 3); da2 = t ? acc[ai][0][m > 0 ? m - 1 : 0][n][2] : Xa[2]; da3 = t ? acc[ai][0][m > 0 ? m - 1 : 0][n][3] : Xa[3];
;                                  db2 = t ? acc[ai][1][m > 0 ? m - 1 : 0][n][2] : Xb[2]; db3 = t ? acc[ai][1][m > 0 ? m - 1 : 0][n][3] : Xb[3]; }
;                     else { da2 = Xa[2]; da3 = Xa[3]; db2 = Xb[2]; db3 = Xb[3]; }
;                     float Ha2 = __builtin_bit_cast(float, __builtin_amdgcn_ds_bpermute(src, __builtin_bit_cast(int, da2)));
;                     float Ha3 = __builtin_bit_cast(float, __builtin_amdgcn_ds_bpermute(src, __builtin_bit_cast(int, da3)));
;                     float Hb2 = __builtin_bit_cast(float, __builtin_amdgcn_ds_bpermute(src, __builtin_bit_cast(int, db2)));
;                     float Hb3 = __builtin_bit_cast(float, __builtin_amdgcn_ds_bpermute(src, __builtin_bit_cast(int, db3)));
;                     if (m == 0) {
;                         float h2a = 0.f, h3a = 0.f, h2b = 0.f, h3b = 0.f;
;                         if (blk > 0) { const PG8_LAS float* hp = halo + ((((blk - 1) * 4 + wc) * 2 + 0) * 2 + n) * 32 + fr; h2a = hp[0]; h3a = hp[16]; h2b = hp[64]; h3b = hp[80]; }
;                         if (fq == 0) { Ha2 = h2a; Ha3 = h3a; Hb2 = h2b; Hb3 = h3b; }
;                     }
;                     const f32x2_t W0 = {wa[n][0], wb[n][0]}, W1 = {wa[n][1], wb[n][1]}, W2 = {wa[n][2], wb[n][2]}, B2 = {ba[n], bb[n]};
;                     const f32x2_t H2 = {Ha2, Hb2}, H3 = {Ha3, Hb3}, X0 = {Xa[0], Xb[0]}, X1 = {Xa[1], Xb[1]}, X2 = {Xa[2], Xb[2]}, X3 = {Xa[3], Xb[3]};
;                     const f32x2_t y0 = B2 + W0 * H2 + W1 * H3 + W2 * X0, y1 = B2 + W0 * H3 + W1 * X0 + W2 * X1, y2 = B2 + W0 * X0 + W1 * X1 + W2 * X2, y3 = B2 + W0 * X1 + W1 * X2 + W2 * X3;
;                     const float ya0 = y0[0], yb0 = y0[1], ya1 = y1[0], yb1 = y1[1], ya2 = y2[0], yb2 = y2[1], ya3 = y3[0], yb3 = y3[1];
;                     o[n][0] = silu_f(ya0) * yb0; o[n][1] = silu_f(ya1) * yb1; o[n][2] = silu_f(ya2) * yb2; o[n][3] = silu_f(ya3) * yb3;
	ds_read_b32 v235, v159 offset:2496
	v_cndmask_b32_e64 v140, v204, v196, s[8:9]
	v_cndmask_b32_e64 v141, v205, v197, s[8:9]
	v_cndmask_b32_e64 v142, v206, v198, s[8:9]
	v_cndmask_b32_e64 v143, v207, v199, s[8:9]
	v_pk_fma_f32 v[164:165], v[238:239], v[140:141], v[250:251] op_sel_hi:[0,1,0]
	v_pk_fma_f32 v[168:169], v[244:245], v[142:143], v[252:253] op_sel_hi:[0,1,0]
	v_pk_fma_f32 v[166:167], v[238:239], v[108:109], v[250:251] op_sel_hi:[0,1,0]
	v_pk_fma_f32 v[170:171], v[244:245], v[104:105], v[252:253] op_sel_hi:[0,1,0]
	v_pk_fma_f32 v[164:165], v[242:243], v[108:109], v[164:165] op_sel_hi:[0,1,1]
	v_pk_fma_f32 v[168:169], v[248:249], v[104:105], v[168:169] op_sel_hi:[0,1,1]
	v_pk_fma_f32 v[166:167], v[242:243], v[110:111], v[166:167] op_sel_hi:[0,1,1]
	v_pk_fma_f32 v[170:171], v[248:249], v[106:107], v[170:171] op_sel_hi:[0,1,1]
	v_fmac_f32_e32 v164, v240, v141
	v_fmac_f32_e32 v168, v246, v143
	v_fmac_f32_e32 v165, v240, v108
	v_fmac_f32_e32 v169, v246, v104
	v_fmac_f32_e32 v166, v240, v109
	v_fmac_f32_e32 v170, v246, v105
	v_fmac_f32_e32 v167, v240, v110
	v_fmac_f32_e32 v171, v246, v106
	v_exp_f32_e32 v144, v164
	v_exp_f32_e32 v145, v165
	v_exp_f32_e32 v146, v166
	v_exp_f32_e32 v147, v167
	v_pk_mul_f32 v[164:165], v[164:165], v[168:169]
	v_pk_mul_f32 v[166:167], v[166:167], v[170:171]
	v_pk_add_f32 v[144:145], v[144:145], v[162:163]
	v_pk_add_f32 v[146:147], v[146:147], v[162:163]
	v_rcp_f32_e32 v144, v144
	v_rcp_f32_e32 v145, v145
	v_rcp_f32_e32 v146, v146
	v_rcp_f32_e32 v147, v147
	v_cndmask_b32_e64 v140, v208, v200, s[8:9]
	v_cndmask_b32_e64 v141, v209, v201, s[8:9]
	v_cndmask_b32_e64 v142, v210, v202, s[8:9]
	v_cndmask_b32_e64 v143, v211, v203, s[8:9]
	v_pk_fma_f32 v[182:183], v[238:239], v[140:141], v[250:251] op_sel:[1,0,1] op_sel_hi:[1,1,1]
	v_pk_fma_f32 v[186:187], v[244:245], v[142:143], v[252:253] op_sel:[1,0,1] op_sel_hi:[1,1,1]
	v_pk_fma_f32 v[184:185], v[238:239], v[100:101], v[250:251] op_sel:[1,0,1] op_sel_hi:[1,1,1]
	v_pk_fma_f32 v[188:189], v[244:245], v[96:97], v[252:253] op_sel:[1,0,1] op_sel_hi:[1,1,1]
	v_pk_fma_f32 v[182:183], v[242:243], v[100:101], v[182:183] op_sel:[1,0,0] op_sel_hi:[1,1,1]
	v_pk_fma_f32 v[186:187], v[248:249], v[96:97], v[186:187] op_sel:[1,0,0] op_sel_hi:[1,1,1]
	v_pk_fma_f32 v[184:185], v[242:243], v[102:103], v[184:185] op_sel:[1,0,0] op_sel_hi:[1,1,1]
	v_pk_fma_f32 v[188:189], v[248:249], v[98:99], v[188:189] op_sel:[1,0,0] op_sel_hi:[1,1,1]
	v_fmac_f32_e32 v182, v241, v141
	v_fmac_f32_e32 v186, v247, v143
	v_fmac_f32_e32 v183, v241, v100
	v_fmac_f32_e32 v187, v247, v96
	v_fmac_f32_e32 v184, v241, v101
	v_fmac_f32_e32 v188, v247, v97
	v_fmac_f32_e32 v185, v241, v102
	v_fmac_f32_e32 v189, v247, v98
	v_exp_f32_e32 v148, v182
	v_exp_f32_e32 v149, v183
	v_exp_f32_e32 v150, v184
	v_exp_f32_e32 v151, v185
	v_pk_mul_f32 v[182:183], v[182:183], v[186:187]
	v_pk_mul_f32 v[184:185], v[184:185], v[188:189]
	v_pk_add_f32 v[148:149], v[148:149], v[162:163]
	v_pk_add_f32 v[150:151], v[150:151], v[162:163]
	v_rcp_f32_e32 v148, v148
	v_rcp_f32_e32 v149, v149
	v_rcp_f32_e32 v150, v150
	v_rcp_f32_e32 v151, v151
	v_pk_mul_f32 v[164:165], v[164:165], v[144:145]
	v_pk_mul_f32 v[166:167], v[166:167], v[146:147]
	v_pk_mul_f32 v[182:183], v[182:183], v[148:149]
	v_pk_mul_f32 v[184:185], v[184:185], v[150:151]
	v_cvt_pk_bf16_f32 v152, v164, v182
	v_cvt_pk_bf16_f32 v153, v165, v183
	v_cvt_pk_bf16_f32 v154, v166, v184
	v_cvt_pk_bf16_f32 v155, v167, v185
	global_store_dword v157, v152, s[76:77]
	s_add_u32 s76, s76, 0x1600
	s_nop 0
	s_addc_u32 s77, s77, 0
	global_store_dword v157, v153, s[76:77]
	s_add_u32 s76, s76, 0x1600
	s_nop 0
	s_addc_u32 s77, s77, 0
	global_store_dword v157, v154, s[76:77]
	s_add_u32 s76, s76, 0x1600
	s_nop 0
	s_addc_u32 s77, s77, 0
	global_store_dword v157, v155, s[76:77]
	s_add_u32 s76, s76, 0x11e00
	s_addc_u32 s77, s77, 0
	s_waitcnt lgkmcnt(13)
	ds_bpermute_b32 v220, v158, v70
	s_nop 0
	s_waitcnt lgkmcnt(13)
	ds_bpermute_b32 v221, v158, v71
	s_nop 0
	s_waitcnt lgkmcnt(13)
	ds_bpermute_b32 v222, v158, v66
	s_nop 0
	s_waitcnt lgkmcnt(13)
	ds_bpermute_b32 v223, v158, v67
	s_nop 0
	s_waitcnt lgkmcnt(13)
	ds_bpermute_b32 v224, v158, v78
	s_nop 0
	s_waitcnt lgkmcnt(13)
	ds_bpermute_b32 v225, v158, v79
	s_nop 0
	s_waitcnt lgkmcnt(13)
	ds_bpermute_b32 v226, v158, v74
	s_nop 0
	s_waitcnt lgkmcnt(13)
;     __device__ __forceinline__ void operator()(const f32x4 (&acc)[2][2][4][2], const Unit& u, int wr, int wc, int fr, int fq) const {
;     ...
;                 for (int n = 0; n < 2; ++n) {
;                     const f32x4 Xa = acc[ai][0][m][n], Xb = acc[ai][1][m][n];
;                     float da2, da3, db2, db3;
;                     if (m > 0) { const bool t = (fq == 3); da2 = t ? acc[ai][0][m > 0 ? m - 1 : 0][n][2] : Xa[2]; da3 = t ? acc[ai][0][m > 0 ? m - 1 : 0][n][3] : Xa[3];
;                                  db2 = t ? acc[ai][1][m > 0 ? m - 1 : 0][n][2] : Xb[2]; db3 = t ? acc[ai][1][m > 0 ? m - 1 : 0][n][3] : Xb[3]; }
;                     else { da2 = Xa[2]; da3 = Xa[3]; db2 = Xb[2]; db3 = Xb[3]; }
;                     float Ha2 = __builtin_bit_cast(float, __builtin_amdgcn_ds_bpermute(src, __builtin_bit_cast(int, da2)));
;                     float Ha3 = __builtin_bit_cast(float, __builtin_amdgcn_ds_bpermute(src, __builtin_bit_cast(int, da3)));
;                     float Hb2 = __builtin_bit_cast(float, __builtin_amdgcn_ds_bpermute(src, __builtin_bit_cast(int, db2)));
;                     float Hb3 = __builtin_bit_cast(float, __builtin_amdgcn_ds_bpermute(src, __builtin_bit_cast(int, db3)));
;                     if (m == 0) {
;                         float h2a = 0.f, h3a = 0.f, h2b = 0.f, h3b = 0.f;
;                         if (blk > 0) { const PG8_LAS float* hp = halo + ((((blk - 1) * 4 + wc) * 2 + 0) * 2 + n) * 32 + fr; h2a = hp[0]; h3a = hp[16]; h2b = hp[64]; h3b = hp[80]; }
;                         if (fq == 0) { Ha2 = h2a; Ha3 = h3a; Hb2 = h2b; Hb3 = h3b; }
;                     }
;                     const f32x2_t W0 = {wa[n][0], wb[n][0]}, W1 = {wa[n][1], wb[n][1]}, W2 = {wa[n][2], wb[n][2]}, B2 = {ba[n], bb[n]};
;                     const f32x2_t H2 = {Ha2, Hb2}, H3 = {Ha3, Hb3}, X0 = {Xa[0], Xb[0]}, X1 = {Xa[1], Xb[1]}, X2 = {Xa[2], Xb[2]}, X3 = {Xa[3], Xb[3]};
;                     const f32x2_t y0 = B2 + W0 * H2 + W1 * H3 + W2 * X0, y1 = B2 + W0 * H3 + W1 * X0 + W2 * X1, y2 = B2 + W0 * X0 + W1 * X1 + W2 * X2, y3 = B2 + W0 * X1 + W1 * X2 + W2 * X3;
;                     const float ya0 = y0[0], yb0 = y0[1], ya1 = y1[0], yb1 = y1[1], ya2 = y2[0], yb2 = y2[1], ya3 = y3[0], yb3 = y3[1];
;                     o[n][0] = silu_f(ya0) * yb0; o[n][1] = silu_f(ya1) * yb1; o[n][2] = silu_f(ya2) * yb2; o[n][3] = silu_f(ya3) * yb3;
	ds_bpermute_b32 v227, v158, v75
	v_cndmask_b32_e64 v140, v212, v204, s[8:9]
	v_cndmask_b32_e64 v141, v213, v205, s[8:9]
	v_cndmask_b32_e64 v142, v214, v206, s[8:9]
	v_cndmask_b32_e64 v143, v215, v207, s[8:9]
	v_pk_fma_f32 v[164:165], v[238:239], v[140:141], v[250:251] op_sel_hi:[0,1,0]
	v_pk_fma_f32 v[168:169], v[244:245], v[142:143], v[252:253] op_sel_hi:[0,1,0]
	v_pk_fma_f32 v[166:167], v[238:239], v[92:93], v[250:251] op_sel_hi:[0,1,0]
	v_pk_fma_f32 v[170:171], v[244:245], v[88:89], v[252:253] op_sel_hi:[0,1,0]
	v_pk_fma_f32 v[164:165], v[242:243], v[92:93], v[164:165] op_sel_hi:[0,1,1]
	v_pk_fma_f32 v[168:169], v[248:249], v[88:89], v[168:169] op_sel_hi:[0,1,1]
	v_pk_fma_f32 v[166:167], v[242:243], v[94:95], v[166:167] op_sel_hi:[0,1,1]
	v_pk_fma_f32 v[170:171], v[248:249], v[90:91], v[170:171] op_sel_hi:[0,1,1]
	v_fmac_f32_e32 v164, v240, v141
	v_fmac_f32_e32 v168, v246, v143
	v_fmac_f32_e32 v165, v240, v92
	v_fmac_f32_e32 v169, v246, v88
	v_fmac_f32_e32 v166, v240, v93
	v_fmac_f32_e32 v170, v246, v89
	v_fmac_f32_e32 v167, v240, v94
	v_fmac_f32_e32 v171, v246, v90
	v_exp_f32_e32 v144, v164
	v_exp_f32_e32 v145, v165
	v_exp_f32_e32 v146, v166
	v_exp_f32_e32 v147, v167
	v_pk_mul_f32 v[164:165], v[164:165], v[168:169]
	v_pk_mul_f32 v[166:167], v[166:167], v[170:171]
	v_pk_add_f32 v[144:145], v[144:145], v[162:163]
	v_pk_add_f32 v[146:147], v[146:147], v[162:163]
	v_rcp_f32_e32 v144, v144
	v_rcp_f32_e32 v145, v145
	v_rcp_f32_e32 v146, v146
	v_rcp_f32_e32 v147, v147
	v_cndmask_b32_e64 v140, v216, v208, s[8:9]
	v_cndmask_b32_e64 v141, v217, v209, s[8:9]
	v_cndmask_b32_e64 v142, v218, v210, s[8:9]
	v_cndmask_b32_e64 v143, v219, v211, s[8:9]
	v_pk_fma_f32 v[182:183], v[238:239], v[140:141], v[250:251] op_sel:[1,0,1] op_sel_hi:[1,1,1]
	v_pk_fma_f32 v[186:187], v[244:245], v[142:143], v[252:253] op_sel:[1,0,1] op_sel_hi:[1,1,1]
	v_pk_fma_f32 v[184:185], v[238:239], v[84:85], v[250:251] op_sel:[1,0,1] op_sel_hi:[1,1,1]
	v_pk_fma_f32 v[188:189], v[244:245], v[80:81], v[252:253] op_sel:[1,0,1] op_sel_hi:[1,1,1]
	v_pk_fma_f32 v[182:183], v[242:243], v[84:85], v[182:183] op_sel:[1,0,0] op_sel_hi:[1,1,1]
	v_pk_fma_f32 v[186:187], v[248:249], v[80:81], v[186:187] op_sel:[1,0,0] op_sel_hi:[1,1,1]
	v_pk_fma_f32 v[184:185], v[242:243], v[86:87], v[184:185] op_sel:[1,0,0] op_sel_hi:[1,1,1]
	v_pk_fma_f32 v[188:189], v[248:249], v[82:83], v[188:189] op_sel:[1,0,0] op_sel_hi:[1,1,1]
	v_fmac_f32_e32 v182, v241, v141
	v_fmac_f32_e32 v186, v247, v143
	v_fmac_f32_e32 v183, v241, v84
	v_fmac_f32_e32 v187, v247, v80
	v_fmac_f32_e32 v184, v241, v85
	v_fmac_f32_e32 v188, v247, v81
	v_fmac_f32_e32 v185, v241, v86
	v_fmac_f32_e32 v189, v247, v82
	v_exp_f32_e32 v148, v182
	v_exp_f32_e32 v149, v183
	v_exp_f32_e32 v150, v184
	v_exp_f32_e32 v151, v185
	v_pk_mul_f32 v[182:183], v[182:183], v[186:187]
	v_pk_mul_f32 v[184:185], v[184:185], v[188:189]
	v_pk_add_f32 v[148:149], v[148:149], v[162:163]
	v_pk_add_f32 v[150:151], v[150:151], v[162:163]
	v_rcp_f32_e32 v148, v148
	v_rcp_f32_e32 v149, v149
	v_rcp_f32_e32 v150, v150
	v_rcp_f32_e32 v151, v151
	v_pk_mul_f32 v[164:165], v[164:165], v[144:145]
	v_pk_mul_f32 v[166:167], v[166:167], v[146:147]
	v_pk_mul_f32 v[182:183], v[182:183], v[148:149]
	v_pk_mul_f32 v[184:185], v[184:185], v[150:151]
	v_cvt_pk_bf16_f32 v152, v164, v182
	v_cvt_pk_bf16_f32 v153, v165, v183
	v_cvt_pk_bf16_f32 v154, v166, v184
	v_cvt_pk_bf16_f32 v155, v167, v185
	global_store_dword v157, v152, s[76:77]
	s_add_u32 s76, s76, 0x1600
	s_nop 0
	s_addc_u32 s77, s77, 0
	global_store_dword v157, v153, s[76:77]
	s_add_u32 s76, s76, 0x1600
	s_nop 0
	s_addc_u32 s77, s77, 0
	global_store_dword v157, v154, s[76:77]
	s_add_u32 s76, s76, 0x1600
	s_nop 0
	s_addc_u32 s77, s77, 0
	global_store_dword v157, v155, s[76:77]
	s_add_u32 s76, s76, 0x11e00
	s_addc_u32 s77, s77, 0
	s_waitcnt lgkmcnt(13)
	ds_bpermute_b32 v196, v158, v62
	s_nop 0
	s_waitcnt lgkmcnt(13)
	ds_bpermute_b32 v197, v158, v63
	s_nop 0
	s_waitcnt lgkmcnt(13)
	ds_bpermute_b32 v198, v158, v58
	s_nop 0
	s_waitcnt lgkmcnt(13)
	ds_bpermute_b32 v199, v158, v59
	s_nop 0
	s_waitcnt lgkmcnt(13)
	ds_bpermute_b32 v200, v158, v54
	s_nop 0
	s_waitcnt lgkmcnt(13)
	ds_bpermute_b32 v201, v158, v55
	s_nop 0
	s_waitcnt lgkmcnt(13)
	ds_bpermute_b32 v202, v158, v50
	s_nop 0
	s_waitcnt lgkmcnt(13)
	ds_bpermute_b32 v203, v158, v51
	s_nop 0
	s_waitcnt lgkmcnt(12)
	v_cndmask_b32_e64 v140, v220, v212, s[8:9]
	v_cndmask_b32_e64 v141, v221, v213, s[8:9]
	v_cndmask_b32_e64 v142, v222, v214, s[8:9]
	v_cndmask_b32_e64 v143, v223, v215, s[8:9]
	v_pk_fma_f32 v[164:165], v[238:239], v[140:141], v[250:251] op_sel_hi:[0,1,0]
	v_pk_fma_f32 v[168:169], v[244:245], v[142:143], v[252:253] op_sel_hi:[0,1,0]
	v_pk_fma_f32 v[166:167], v[238:239], v[68:69], v[250:251] op_sel_hi:[0,1,0]
	v_pk_fma_f32 v[170:171], v[244:245], v[64:65], v[252:253] op_sel_hi:[0,1,0]
	v_pk_fma_f32 v[164:165], v[242:243], v[68:69], v[164:165] op_sel_hi:[0,1,1]
	v_pk_fma_f32 v[168:169], v[248:249], v[64:65], v[168:169] op_sel_hi:[0,1,1]
	v_pk_fma_f32 v[166:167], v[242:243], v[70:71], v[166:167] op_sel_hi:[0,1,1]
	v_pk_fma_f32 v[170:171], v[248:249], v[66:67], v[170:171] op_sel_hi:[0,1,1]
	v_fmac_f32_e32 v164, v240, v141
	v_fmac_f32_e32 v168, v246, v143
	v_fmac_f32_e32 v165, v240, v68
	v_fmac_f32_e32 v169, v246, v64
	v_fmac_f32_e32 v166, v240, v69
	v_fmac_f32_e32 v170, v246, v65
	v_fmac_f32_e32 v167, v240, v70
	v_fmac_f32_e32 v171, v246, v66
	v_exp_f32_e32 v144, v164
	v_exp_f32_e32 v145, v165
	v_exp_f32_e32 v146, v166
	v_exp_f32_e32 v147, v167
	v_pk_mul_f32 v[164:165], v[164:165], v[168:169]
	v_pk_mul_f32 v[166:167], v[166:167], v[170:171]
	v_pk_add_f32 v[144:145], v[144:145], v[162:163]
	v_pk_add_f32 v[146:147], v[146:147], v[162:163]
	v_rcp_f32_e32 v144, v144
	v_rcp_f32_e32 v145, v145
	v_rcp_f32_e32 v146, v146
	v_rcp_f32_e64 v147, v147
	s_waitcnt lgkmcnt(8)
;     __device__ __forceinline__ void operator()(const f32x4 (&acc)[2][2][4][2], const Unit& u, int wr, int wc, int fr, int fq) const {
;     ...
;                 for (int n = 0; n < 2; ++n) {
;                     const f32x4 Xa = acc[ai][0][m][n], Xb = acc[ai][1][m][n];
;                     float da2, da3, db2, db3;
;                     if (m > 0) { const bool t = (fq == 3); da2 = t ? acc[ai][0][m > 0 ? m - 1 : 0][n][2] : Xa[2]; da3 = t ? acc[ai][0][m > 0 ? m - 1 : 0][n][3] : Xa[3];
;                                  db2 = t ? acc[ai][1][m > 0 ? m - 1 : 0][n][2] : Xb[2]; db3 = t ? acc[ai][1][m > 0 ? m - 1 : 0][n][3] : Xb[3]; }
;                     else { da2 = Xa[2]; da3 = Xa[3]; db2 = Xb[2]; db3 = Xb[3]; }
;                     float Ha2 = __builtin_bit_cast(float, __builtin_amdgcn_ds_bpermute(src, __builtin_bit_cast(int, da2)));
;                     float Ha3 = __builtin_bit_cast(float, __builtin_amdgcn_ds_bpermute(src, __builtin_bit_cast(int, da3)));
;                     float Hb2 = __builtin_bit_cast(float, __builtin_amdgcn_ds_bpermute(src, __builtin_bit_cast(int, db2)));
;                     float Hb3 = __builtin_bit_cast(float, __builtin_amdgcn_ds_bpermute(src, __builtin_bit_cast(int, db3)));
;                     if (m == 0) {
;                         float h2a = 0.f, h3a = 0.f, h2b = 0.f, h3b = 0.f;
;                         if (blk > 0) { const PG8_LAS float* hp = halo + ((((blk - 1) * 4 + wc) * 2 + 0) * 2 + n) * 32 + fr; h2a = hp[0]; h3a = hp[16]; h2b = hp[64]; h3b = hp[80]; }
;                         if (fq == 0) { Ha2 = h2a; Ha3 = h3a; Hb2 = h2b; Hb3 = h3b; }
;                     }
;                     const f32x2_t W0 = {wa[n][0], wb[n][0]}, W1 = {wa[n][1], wb[n][1]}, W2 = {wa[n][2], wb[n][2]}, B2 = {ba[n], bb[n]};
;                     const f32x2_t H2 = {Ha2, Hb2}, H3 = {Ha3, Hb3}, X0 = {Xa[0], Xb[0]}, X1 = {Xa[1], Xb[1]}, X2 = {Xa[2], Xb[2]}, X3 = {Xa[3], Xb[3]};
;                     const f32x2_t y0 = B2 + W0 * H2 + W1 * H3 + W2 * X0, y1 = B2 + W0 * H3 + W1 * X0 + W2 * X1, y2 = B2 + W0 * X0 + W1 * X1 + W2 * X2, y3 = B2 + W0 * X1 + W1 * X2 + W2 * X3;
;                     const float ya0 = y0[0], yb0 = y0[1], ya1 = y1[0], yb1 = y1[1], ya2 = y2[0], yb2 = y2[1], ya3 = y3[0], yb3 = y3[1];
;                     o[n][0] = silu_f(ya0) * yb0; o[n][1] = silu_f(ya1) * yb1; o[n][2] = silu_f(ya2) * yb2; o[n][3] = silu_f(ya3) * yb3;
	v_cndmask_b32_e64 v140, v224, v216, s[8:9]
	v_cndmask_b32_e64 v141, v225, v217, s[8:9]
	v_cndmask_b32_e64 v142, v226, v218, s[8:9]
	v_cndmask_b32_e64 v143, v227, v219, s[8:9]
	v_pk_fma_f32 v[182:183], v[238:239], v[140:141], v[250:251] op_sel:[1,0,1] op_sel_hi:[1,1,1]
	v_pk_fma_f32 v[186:187], v[244:245], v[142:143], v[252:253] op_sel:[1,0,1] op_sel_hi:[1,1,1]
	v_pk_fma_f32 v[184:185], v[238:239], v[76:77], v[250:251] op_sel:[1,0,1] op_sel_hi:[1,1,1]
	v_pk_fma_f32 v[188:189], v[244:245], v[72:73], v[252:253] op_sel:[1,0,1] op_sel_hi:[1,1,1]
	v_pk_fma_f32 v[182:183], v[242:243], v[76:77], v[182:183] op_sel:[1,0,0] op_sel_hi:[1,1,1]
	v_pk_fma_f32 v[186:187], v[248:249], v[72:73], v[186:187] op_sel:[1,0,0] op_sel_hi:[1,1,1]
	v_pk_fma_f32 v[184:185], v[242:243], v[78:79], v[184:185] op_sel:[1,0,0] op_sel_hi:[1,1,1]
	v_pk_fma_f32 v[188:189], v[248:249], v[74:75], v[188:189] op_sel:[1,0,0] op_sel_hi:[1,1,1]
	v_fmac_f32_e32 v182, v241, v141
	v_fmac_f32_e32 v186, v247, v143
	v_fmac_f32_e32 v183, v241, v76
	v_fmac_f32_e32 v187, v247, v72
	v_fmac_f32_e32 v184, v241, v77
	v_fmac_f32_e32 v188, v247, v73
	v_fmac_f32_e32 v185, v241, v78
	v_fmac_f32_e32 v189, v247, v74
	v_exp_f32_e32 v148, v182
	v_exp_f32_e32 v149, v183
	v_exp_f32_e32 v150, v184
	v_exp_f32_e32 v151, v185
	v_pk_mul_f32 v[182:183], v[182:183], v[186:187]
	v_pk_mul_f32 v[184:185], v[184:185], v[188:189]
	v_pk_add_f32 v[148:149], v[148:149], v[162:163]
	v_pk_add_f32 v[150:151], v[150:151], v[162:163]
	v_rcp_f32_e32 v148, v148
	v_rcp_f32_e32 v149, v149
	v_rcp_f32_e32 v150, v150
	v_rcp_f32_e32 v151, v151
	v_pk_mul_f32 v[164:165], v[164:165], v[144:145]
	v_pk_mul_f32 v[166:167], v[166:167], v[146:147]
	v_pk_mul_f32 v[182:183], v[182:183], v[148:149]
	v_pk_mul_f32 v[184:185], v[184:185], v[150:151]
	v_cvt_pk_bf16_f32 v152, v164, v182
	v_cvt_pk_bf16_f32 v153, v165, v183
	v_cvt_pk_bf16_f32 v154, v166, v184
	v_cvt_pk_bf16_f32 v155, v167, v185
	global_store_dword v157, v152, s[76:77]
	s_add_u32 s76, s76, 0x1600
	s_nop 0
	s_addc_u32 s77, s77, 0
	global_store_dword v157, v153, s[76:77]
	s_add_u32 s76, s76, 0x1600
	s_nop 0
	s_addc_u32 s77, s77, 0
	global_store_dword v157, v154, s[76:77]
	s_add_u32 s76, s76, 0x1600
	s_nop 0
	s_addc_u32 s77, s77, 0
	global_store_dword v157, v155, s[76:77]
	s_add_u32 s76, s76, 0x69e00
	s_nop 0
	s_addc_u32 s77, s77, 0
	ds_bpermute_b32 v204, v158, v46
	ds_bpermute_b32 v205, v158, v47
	ds_bpermute_b32 v206, v158, v42
	ds_bpermute_b32 v207, v158, v43
	ds_bpermute_b32 v208, v158, v38
	ds_bpermute_b32 v209, v158, v39
	s_nop 0
	s_waitcnt lgkmcnt(13)
	ds_bpermute_b32 v210, v158, v34
	s_nop 0
	s_waitcnt lgkmcnt(13)
	ds_bpermute_b32 v211, v158, v35
	s_nop 0
	s_waitcnt lgkmcnt(12)
	v_cndmask_b32_e64 v140, v196, v228, s[8:9]
	v_cndmask_b32_e64 v141, v197, v229, s[8:9]
	v_cndmask_b32_e64 v142, v198, v230, s[8:9]
	v_cndmask_b32_e64 v143, v199, v231, s[8:9]
	v_pk_fma_f32 v[164:165], v[238:239], v[140:141], v[250:251] op_sel_hi:[0,1,0]
	v_pk_fma_f32 v[168:169], v[244:245], v[142:143], v[252:253] op_sel_hi:[0,1,0]
	v_pk_fma_f32 v[166:167], v[238:239], v[60:61], v[250:251] op_sel_hi:[0,1,0]
	v_pk_fma_f32 v[170:171], v[244:245], v[56:57], v[252:253] op_sel_hi:[0,1,0]
	v_pk_fma_f32 v[164:165], v[242:243], v[60:61], v[164:165] op_sel_hi:[0,1,1]
	v_pk_fma_f32 v[168:169], v[248:249], v[56:57], v[168:169] op_sel_hi:[0,1,1]
	v_pk_fma_f32 v[166:167], v[242:243], v[62:63], v[166:167] op_sel_hi:[0,1,1]
	v_pk_fma_f32 v[170:171], v[248:249], v[58:59], v[170:171] op_sel_hi:[0,1,1]
	v_fmac_f32_e32 v164, v240, v141
	v_fmac_f32_e32 v168, v246, v143
	v_fmac_f32_e32 v165, v240, v60
	v_fmac_f32_e32 v169, v246, v56
	v_fmac_f32_e32 v166, v240, v61
	v_fmac_f32_e32 v170, v246, v57
	v_fmac_f32_e32 v167, v240, v62
	v_fmac_f32_e32 v171, v246, v58
	v_exp_f32_e32 v144, v164
	v_exp_f32_e32 v145, v165
	v_exp_f32_e32 v146, v166
	v_exp_f32_e32 v147, v167
	v_pk_mul_f32 v[164:165], v[164:165], v[168:169]
	v_pk_mul_f32 v[166:167], v[166:167], v[170:171]
	v_pk_add_f32 v[144:145], v[144:145], v[162:163]
	v_pk_add_f32 v[146:147], v[146:147], v[162:163]
	v_rcp_f32_e32 v144, v144
	v_rcp_f32_e32 v145, v145
	v_rcp_f32_e32 v146, v146
	v_rcp_f32_e64 v147, v147
	s_waitcnt lgkmcnt(8)
	v_cndmask_b32_e64 v140, v200, v232, s[8:9]
	v_cndmask_b32_e64 v141, v201, v233, s[8:9]
	v_cndmask_b32_e64 v142, v202, v234, s[8:9]
	v_cndmask_b32_e64 v143, v203, v235, s[8:9]
	v_pk_fma_f32 v[182:183], v[238:239], v[140:141], v[250:251] op_sel:[1,0,1] op_sel_hi:[1,1,1]
	v_pk_fma_f32 v[186:187], v[244:245], v[142:143], v[252:253] op_sel:[1,0,1] op_sel_hi:[1,1,1]
	v_pk_fma_f32 v[184:185], v[238:239], v[52:53], v[250:251] op_sel:[1,0,1] op_sel_hi:[1,1,1]
	v_pk_fma_f32 v[188:189], v[244:245], v[48:49], v[252:253] op_sel:[1,0,1] op_sel_hi:[1,1,1]
	v_pk_fma_f32 v[182:183], v[242:243], v[52:53], v[182:183] op_sel:[1,0,0] op_sel_hi:[1,1,1]
	v_pk_fma_f32 v[186:187], v[248:249], v[48:49], v[186:187] op_sel:[1,0,0] op_sel_hi:[1,1,1]
	v_pk_fma_f32 v[184:185], v[242:243], v[54:55], v[184:185] op_sel:[1,0,0] op_sel_hi:[1,1,1]
	v_pk_fma_f32 v[188:189], v[248:249], v[50:51], v[188:189] op_sel:[1,0,0] op_sel_hi:[1,1,1]
	v_fmac_f32_e32 v182, v241, v141
	v_fmac_f32_e32 v186, v247, v143
	v_fmac_f32_e32 v183, v241, v52
	v_fmac_f32_e32 v187, v247, v48
	v_fmac_f32_e32 v184, v241, v53
	v_fmac_f32_e32 v188, v247, v49
	v_fmac_f32_e32 v185, v241, v54
	v_fmac_f32_e32 v189, v247, v50
	v_exp_f32_e32 v148, v182
	v_exp_f32_e32 v149, v183
	v_exp_f32_e32 v150, v184
	v_exp_f32_e32 v151, v185
	v_pk_mul_f32 v[182:183], v[182:183], v[186:187]
	v_pk_mul_f32 v[184:185], v[184:185], v[188:189]
	v_pk_add_f32 v[148:149], v[148:149], v[162:163]
	v_pk_add_f32 v[150:151], v[150:151], v[162:163]
	v_rcp_f32_e32 v148, v148
	v_rcp_f32_e32 v149, v149
	v_rcp_f32_e32 v150, v150
	v_rcp_f32_e32 v151, v151
	v_pk_mul_f32 v[164:165], v[164:165], v[144:145]
	v_pk_mul_f32 v[166:167], v[166:167], v[146:147]
	v_pk_mul_f32 v[182:183], v[182:183], v[148:149]
	v_pk_mul_f32 v[184:185], v[184:185], v[150:151]
	v_cvt_pk_bf16_f32 v152, v164, v182
	v_cvt_pk_bf16_f32 v153, v165, v183
	v_cvt_pk_bf16_f32 v154, v166, v184
	v_cvt_pk_bf16_f32 v155, v167, v185
	global_store_dword v157, v152, s[76:77]
	s_add_u32 s76, s76, 0x1600
	s_nop 0
	s_addc_u32 s77, s77, 0
	global_store_dword v157, v153, s[76:77]
	s_add_u32 s76, s76, 0x1600
	s_nop 0
	s_addc_u32 s77, s77, 0
	global_store_dword v157, v154, s[76:77]
	s_add_u32 s76, s76, 0x1600
	s_nop 0
	s_addc_u32 s77, s77, 0
	global_store_dword v157, v155, s[76:77]
	s_add_u32 s76, s76, 0x11e00
	s_nop 0
	s_addc_u32 s77, s77, 0
	ds_bpermute_b32 v212, v158, v30
	ds_bpermute_b32 v213, v158, v31
	ds_bpermute_b32 v214, v158, v26
	ds_bpermute_b32 v215, v158, v27
	ds_bpermute_b32 v216, v158, v22
	ds_bpermute_b32 v217, v158, v23
	s_nop 0
	s_waitcnt lgkmcnt(13)
;     __device__ __forceinline__ void operator()(const f32x4 (&acc)[2][2][4][2], const Unit& u, int wr, int wc, int fr, int fq) const {
;     ...
;                 for (int n = 0; n < 2; ++n) {
;                     const f32x4 Xa = acc[ai][0][m][n], Xb = acc[ai][1][m][n];
;                     float da2, da3, db2, db3;
;                     if (m > 0) { const bool t = (fq == 3); da2 = t ? acc[ai][0][m > 0 ? m - 1 : 0][n][2] : Xa[2]; da3 = t ? acc[ai][0][m > 0 ? m - 1 : 0][n][3] : Xa[3];
;                                  db2 = t ? acc[ai][1][m > 0 ? m - 1 : 0][n][2] : Xb[2]; db3 = t ? acc[ai][1][m > 0 ? m - 1 : 0][n][3] : Xb[3]; }
;                     else { da2 = Xa[2]; da3 = Xa[3]; db2 = Xb[2]; db3 = Xb[3]; }
;                     float Ha2 = __builtin_bit_cast(float, __builtin_amdgcn_ds_bpermute(src, __builtin_bit_cast(int, da2)));
;                     float Ha3 = __builtin_bit_cast(float, __builtin_amdgcn_ds_bpermute(src, __builtin_bit_cast(int, da3)));
;                     float Hb2 = __builtin_bit_cast(float, __builtin_amdgcn_ds_bpermute(src, __builtin_bit_cast(int, db2)));
;                     float Hb3 = __builtin_bit_cast(float, __builtin_amdgcn_ds_bpermute(src, __builtin_bit_cast(int, db3)));
;                     if (m == 0) {
;                         float h2a = 0.f, h3a = 0.f, h2b = 0.f, h3b = 0.f;
;                         if (blk > 0) { const PG8_LAS float* hp = halo + ((((blk - 1) * 4 + wc) * 2 + 0) * 2 + n) * 32 + fr; h2a = hp[0]; h3a = hp[16]; h2b = hp[64]; h3b = hp[80]; }
;                         if (fq == 0) { Ha2 = h2a; Ha3 = h3a; Hb2 = h2b; Hb3 = h3b; }
;                     }
;                     const f32x2_t W0 = {wa[n][0], wb[n][0]}, W1 = {wa[n][1], wb[n][1]}, W2 = {wa[n][2], wb[n][2]}, B2 = {ba[n], bb[n]};
;                     const f32x2_t H2 = {Ha2, Hb2}, H3 = {Ha3, Hb3}, X0 = {Xa[0], Xb[0]}, X1 = {Xa[1], Xb[1]}, X2 = {Xa[2], Xb[2]}, X3 = {Xa[3], Xb[3]};
;                     const f32x2_t y0 = B2 + W0 * H2 + W1 * H3 + W2 * X0, y1 = B2 + W0 * H3 + W1 * X0 + W2 * X1, y2 = B2 + W0 * X0 + W1 * X1 + W2 * X2, y3 = B2 + W0 * X1 + W1 * X2 + W2 * X3;
;                     const float ya0 = y0[0], yb0 = y0[1], ya1 = y1[0], yb1 = y1[1], ya2 = y2[0], yb2 = y2[1], ya3 = y3[0], yb3 = y3[1];
;                     o[n][0] = silu_f(ya0) * yb0; o[n][1] = silu_f(ya1) * yb1; o[n][2] = silu_f(ya2) * yb2; o[n][3] = silu_f(ya3) * yb3;
	ds_bpermute_b32 v218, v158, v18
	s_nop 0
	s_waitcnt lgkmcnt(13)
	ds_bpermute_b32 v219, v158, v19
	s_nop 0
	s_waitcnt lgkmcnt(12)
	v_cndmask_b32_e64 v140, v204, v196, s[8:9]
	v_cndmask_b32_e64 v141, v205, v197, s[8:9]
	v_cndmask_b32_e64 v142, v206, v198, s[8:9]
	v_cndmask_b32_e64 v143, v207, v199, s[8:9]
	v_pk_fma_f32 v[164:165], v[238:239], v[140:141], v[250:251] op_sel_hi:[0,1,0]
	v_pk_fma_f32 v[168:169], v[244:245], v[142:143], v[252:253] op_sel_hi:[0,1,0]
	v_pk_fma_f32 v[166:167], v[238:239], v[44:45], v[250:251] op_sel_hi:[0,1,0]
	v_pk_fma_f32 v[170:171], v[244:245], v[40:41], v[252:253] op_sel_hi:[0,1,0]
	v_pk_fma_f32 v[164:165], v[242:243], v[44:45], v[164:165] op_sel_hi:[0,1,1]
	v_pk_fma_f32 v[168:169], v[248:249], v[40:41], v[168:169] op_sel_hi:[0,1,1]
	v_pk_fma_f32 v[166:167], v[242:243], v[46:47], v[166:167] op_sel_hi:[0,1,1]
	v_pk_fma_f32 v[170:171], v[248:249], v[42:43], v[170:171] op_sel_hi:[0,1,1]
	v_fmac_f32_e32 v164, v240, v141
	v_fmac_f32_e32 v168, v246, v143
	v_fmac_f32_e32 v165, v240, v44
	v_fmac_f32_e32 v169, v246, v40
	v_fmac_f32_e32 v166, v240, v45
	v_fmac_f32_e32 v170, v246, v41
	v_fmac_f32_e32 v167, v240, v46
	v_fmac_f32_e32 v171, v246, v42
	v_exp_f32_e32 v144, v164
	v_exp_f32_e32 v145, v165
	v_exp_f32_e32 v146, v166
	v_exp_f32_e32 v147, v167
	v_pk_mul_f32 v[164:165], v[164:165], v[168:169]
	v_pk_mul_f32 v[166:167], v[166:167], v[170:171]
	v_pk_add_f32 v[144:145], v[144:145], v[162:163]
	v_pk_add_f32 v[146:147], v[146:147], v[162:163]
	v_rcp_f32_e32 v144, v144
	v_rcp_f32_e32 v145, v145
	v_rcp_f32_e32 v146, v146
	v_rcp_f32_e64 v147, v147
	s_waitcnt lgkmcnt(8)
	v_cndmask_b32_e64 v140, v208, v200, s[8:9]
	v_cndmask_b32_e64 v141, v209, v201, s[8:9]
	v_cndmask_b32_e64 v142, v210, v202, s[8:9]
	v_cndmask_b32_e64 v143, v211, v203, s[8:9]
	v_pk_fma_f32 v[182:183], v[238:239], v[140:141], v[250:251] op_sel:[1,0,1] op_sel_hi:[1,1,1]
	v_pk_fma_f32 v[186:187], v[244:245], v[142:143], v[252:253] op_sel:[1,0,1] op_sel_hi:[1,1,1]
	v_pk_fma_f32 v[184:185], v[238:239], v[36:37], v[250:251] op_sel:[1,0,1] op_sel_hi:[1,1,1]
	v_pk_fma_f32 v[188:189], v[244:245], v[32:33], v[252:253] op_sel:[1,0,1] op_sel_hi:[1,1,1]
	v_pk_fma_f32 v[182:183], v[242:243], v[36:37], v[182:183] op_sel:[1,0,0] op_sel_hi:[1,1,1]
	v_pk_fma_f32 v[186:187], v[248:249], v[32:33], v[186:187] op_sel:[1,0,0] op_sel_hi:[1,1,1]
	v_pk_fma_f32 v[184:185], v[242:243], v[38:39], v[184:185] op_sel:[1,0,0] op_sel_hi:[1,1,1]
	v_pk_fma_f32 v[188:189], v[248:249], v[34:35], v[188:189] op_sel:[1,0,0] op_sel_hi:[1,1,1]
	v_fmac_f32_e32 v182, v241, v141
	v_fmac_f32_e32 v186, v247, v143
	v_fmac_f32_e32 v183, v241, v36
	v_fmac_f32_e32 v187, v247, v32
	v_fmac_f32_e32 v184, v241, v37
	v_fmac_f32_e32 v188, v247, v33
	v_fmac_f32_e32 v185, v241, v38
	v_fmac_f32_e32 v189, v247, v34
	v_exp_f32_e32 v148, v182
	v_exp_f32_e32 v149, v183
	v_exp_f32_e32 v150, v184
	v_exp_f32_e32 v151, v185
	v_pk_mul_f32 v[182:183], v[182:183], v[186:187]
	v_pk_mul_f32 v[184:185], v[184:185], v[188:189]
	v_pk_add_f32 v[148:149], v[148:149], v[162:163]
	v_pk_add_f32 v[150:151], v[150:151], v[162:163]
	v_rcp_f32_e32 v148, v148
	v_rcp_f32_e32 v149, v149
	v_rcp_f32_e32 v150, v150
	v_rcp_f32_e32 v151, v151
	v_pk_mul_f32 v[164:165], v[164:165], v[144:145]
	v_pk_mul_f32 v[166:167], v[166:167], v[146:147]
	v_pk_mul_f32 v[182:183], v[182:183], v[148:149]
	v_pk_mul_f32 v[184:185], v[184:185], v[150:151]
	v_cvt_pk_bf16_f32 v152, v164, v182
	v_cvt_pk_bf16_f32 v153, v165, v183
	v_cvt_pk_bf16_f32 v154, v166, v184
	v_cvt_pk_bf16_f32 v155, v167, v185
	global_store_dword v157, v152, s[76:77]
	s_add_u32 s76, s76, 0x1600
	s_nop 0
	s_addc_u32 s77, s77, 0
	global_store_dword v157, v153, s[76:77]
	s_add_u32 s76, s76, 0x1600
	s_nop 0
	s_addc_u32 s77, s77, 0
	global_store_dword v157, v154, s[76:77]
	s_add_u32 s76, s76, 0x1600
	s_nop 0
	s_addc_u32 s77, s77, 0
	global_store_dword v157, v155, s[76:77]
	s_add_u32 s76, s76, 0x11e00
	s_nop 0
	s_addc_u32 s77, s77, 0
	ds_bpermute_b32 v220, v158, v2
	ds_bpermute_b32 v221, v158, v3
	ds_bpermute_b32 v222, v158, v6
	ds_bpermute_b32 v223, v158, v7
	ds_bpermute_b32 v224, v158, v14
	ds_bpermute_b32 v225, v158, v15
	s_nop 0
	s_waitcnt lgkmcnt(13)
	ds_bpermute_b32 v226, v158, v10
	s_nop 0
	s_waitcnt lgkmcnt(13)
	ds_bpermute_b32 v227, v158, v11
	s_nop 0
	s_waitcnt lgkmcnt(12)
	v_cndmask_b32_e64 v140, v212, v204, s[8:9]
	v_cndmask_b32_e64 v141, v213, v205, s[8:9]
	v_cndmask_b32_e64 v142, v214, v206, s[8:9]
	v_cndmask_b32_e64 v143, v215, v207, s[8:9]
	v_pk_fma_f32 v[164:165], v[238:239], v[140:141], v[250:251] op_sel_hi:[0,1,0]
	v_pk_fma_f32 v[168:169], v[244:245], v[142:143], v[252:253] op_sel_hi:[0,1,0]
	v_pk_fma_f32 v[166:167], v[238:239], v[28:29], v[250:251] op_sel_hi:[0,1,0]
	v_pk_fma_f32 v[170:171], v[244:245], v[24:25], v[252:253] op_sel_hi:[0,1,0]
	v_pk_fma_f32 v[164:165], v[242:243], v[28:29], v[164:165] op_sel_hi:[0,1,1]
	v_pk_fma_f32 v[168:169], v[248:249], v[24:25], v[168:169] op_sel_hi:[0,1,1]
	v_pk_fma_f32 v[166:167], v[242:243], v[30:31], v[166:167] op_sel_hi:[0,1,1]
	v_pk_fma_f32 v[170:171], v[248:249], v[26:27], v[170:171] op_sel_hi:[0,1,1]
	v_fmac_f32_e32 v164, v240, v141
	v_fmac_f32_e32 v168, v246, v143
	v_fmac_f32_e32 v165, v240, v28
	v_fmac_f32_e32 v169, v246, v24
	v_fmac_f32_e32 v166, v240, v29
	v_fmac_f32_e32 v170, v246, v25
	v_fmac_f32_e32 v167, v240, v30
	v_fmac_f32_e32 v171, v246, v26
	v_exp_f32_e32 v144, v164
	v_exp_f32_e32 v145, v165
	v_exp_f32_e32 v146, v166
	v_exp_f32_e32 v147, v167
	v_pk_mul_f32 v[164:165], v[164:165], v[168:169]
	v_pk_mul_f32 v[166:167], v[166:167], v[170:171]
	v_pk_add_f32 v[144:145], v[144:145], v[162:163]
	v_pk_add_f32 v[146:147], v[146:147], v[162:163]
	v_rcp_f32_e32 v144, v144
	v_rcp_f32_e32 v145, v145
	v_rcp_f32_e32 v146, v146
	v_rcp_f32_e64 v147, v147
	s_waitcnt lgkmcnt(8)
;     __device__ __forceinline__ void operator()(const f32x4 (&acc)[2][2][4][2], const Unit& u, int wr, int wc, int fr, int fq) const {
;     ...
;                 for (int n = 0; n < 2; ++n) {
;                     const f32x4 Xa = acc[ai][0][m][n], Xb = acc[ai][1][m][n];
;                     float da2, da3, db2, db3;
;                     if (m > 0) { const bool t = (fq == 3); da2 = t ? acc[ai][0][m > 0 ? m - 1 : 0][n][2] : Xa[2]; da3 = t ? acc[ai][0][m > 0 ? m - 1 : 0][n][3] : Xa[3];
;                                  db2 = t ? acc[ai][1][m > 0 ? m - 1 : 0][n][2] : Xb[2]; db3 = t ? acc[ai][1][m > 0 ? m - 1 : 0][n][3] : Xb[3]; }
;                     else { da2 = Xa[2]; da3 = Xa[3]; db2 = Xb[2]; db3 = Xb[3]; }
;                     float Ha2 = __builtin_bit_cast(float, __builtin_amdgcn_ds_bpermute(src, __builtin_bit_cast(int, da2)));
;                     float Ha3 = __builtin_bit_cast(float, __builtin_amdgcn_ds_bpermute(src, __builtin_bit_cast(int, da3)));
;                     float Hb2 = __builtin_bit_cast(float, __builtin_amdgcn_ds_bpermute(src, __builtin_bit_cast(int, db2)));
;                     float Hb3 = __builtin_bit_cast(float, __builtin_amdgcn_ds_bpermute(src, __builtin_bit_cast(int, db3)));
;                     if (m == 0) {
;                         float h2a = 0.f, h3a = 0.f, h2b = 0.f, h3b = 0.f;
;                         if (blk > 0) { const PG8_LAS float* hp = halo + ((((blk - 1) * 4 + wc) * 2 + 0) * 2 + n) * 32 + fr; h2a = hp[0]; h3a = hp[16]; h2b = hp[64]; h3b = hp[80]; }
;                         if (fq == 0) { Ha2 = h2a; Ha3 = h3a; Hb2 = h2b; Hb3 = h3b; }
;                     }
;                     const f32x2_t W0 = {wa[n][0], wb[n][0]}, W1 = {wa[n][1], wb[n][1]}, W2 = {wa[n][2], wb[n][2]}, B2 = {ba[n], bb[n]};
;                     const f32x2_t H2 = {Ha2, Hb2}, H3 = {Ha3, Hb3}, X0 = {Xa[0], Xb[0]}, X1 = {Xa[1], Xb[1]}, X2 = {Xa[2], Xb[2]}, X3 = {Xa[3], Xb[3]};
;                     const f32x2_t y0 = B2 + W0 * H2 + W1 * H3 + W2 * X0, y1 = B2 + W0 * H3 + W1 * X0 + W2 * X1, y2 = B2 + W0 * X0 + W1 * X1 + W2 * X2, y3 = B2 + W0 * X1 + W1 * X2 + W2 * X3;
;                     const float ya0 = y0[0], yb0 = y0[1], ya1 = y1[0], yb1 = y1[1], ya2 = y2[0], yb2 = y2[1], ya3 = y3[0], yb3 = y3[1];
;                     o[n][0] = silu_f(ya0) * yb0; o[n][1] = silu_f(ya1) * yb1; o[n][2] = silu_f(ya2) * yb2; o[n][3] = silu_f(ya3) * yb3;
	v_cndmask_b32_e64 v140, v216, v208, s[8:9]
	v_cndmask_b32_e64 v141, v217, v209, s[8:9]
	v_cndmask_b32_e64 v142, v218, v210, s[8:9]
	v_cndmask_b32_e64 v143, v219, v211, s[8:9]
	v_pk_fma_f32 v[182:183], v[238:239], v[140:141], v[250:251] op_sel:[1,0,1] op_sel_hi:[1,1,1]
	v_pk_fma_f32 v[186:187], v[244:245], v[142:143], v[252:253] op_sel:[1,0,1] op_sel_hi:[1,1,1]
	v_pk_fma_f32 v[184:185], v[238:239], v[20:21], v[250:251] op_sel:[1,0,1] op_sel_hi:[1,1,1]
	v_pk_fma_f32 v[188:189], v[244:245], v[16:17], v[252:253] op_sel:[1,0,1] op_sel_hi:[1,1,1]
	v_pk_fma_f32 v[182:183], v[242:243], v[20:21], v[182:183] op_sel:[1,0,0] op_sel_hi:[1,1,1]
	v_pk_fma_f32 v[186:187], v[248:249], v[16:17], v[186:187] op_sel:[1,0,0] op_sel_hi:[1,1,1]
	v_pk_fma_f32 v[184:185], v[242:243], v[22:23], v[184:185] op_sel:[1,0,0] op_sel_hi:[1,1,1]
	v_pk_fma_f32 v[188:189], v[248:249], v[18:19], v[188:189] op_sel:[1,0,0] op_sel_hi:[1,1,1]
	v_fmac_f32_e32 v182, v241, v141
	v_fmac_f32_e32 v186, v247, v143
	v_fmac_f32_e32 v183, v241, v20
	v_fmac_f32_e32 v187, v247, v16
	v_fmac_f32_e32 v184, v241, v21
	v_fmac_f32_e32 v188, v247, v17
	v_fmac_f32_e32 v185, v241, v22
	v_fmac_f32_e32 v189, v247, v18
	v_exp_f32_e32 v148, v182
	v_exp_f32_e32 v149, v183
	v_exp_f32_e32 v150, v184
	v_exp_f32_e32 v151, v185
	v_pk_mul_f32 v[182:183], v[182:183], v[186:187]
	v_pk_mul_f32 v[184:185], v[184:185], v[188:189]
	v_pk_add_f32 v[148:149], v[148:149], v[162:163]
	v_pk_add_f32 v[150:151], v[150:151], v[162:163]
	v_rcp_f32_e32 v148, v148
	v_rcp_f32_e32 v149, v149
	v_rcp_f32_e32 v150, v150
	v_rcp_f32_e32 v151, v151
	v_pk_mul_f32 v[164:165], v[164:165], v[144:145]
	v_pk_mul_f32 v[166:167], v[166:167], v[146:147]
	v_pk_mul_f32 v[182:183], v[182:183], v[148:149]
	v_pk_mul_f32 v[184:185], v[184:185], v[150:151]
	v_cvt_pk_bf16_f32 v152, v164, v182
	v_cvt_pk_bf16_f32 v153, v165, v183
	v_cvt_pk_bf16_f32 v154, v166, v184
	v_cvt_pk_bf16_f32 v155, v167, v185
	global_store_dword v157, v152, s[76:77]
	s_add_u32 s76, s76, 0x1600
	s_nop 0
	s_addc_u32 s77, s77, 0
	global_store_dword v157, v153, s[76:77]
	s_add_u32 s76, s76, 0x1600
	s_nop 0
	s_addc_u32 s77, s77, 0
	global_store_dword v157, v154, s[76:77]
	s_add_u32 s76, s76, 0x1600
	s_nop 0
	s_addc_u32 s77, s77, 0
	global_store_dword v157, v155, s[76:77]
	s_add_u32 s76, s76, 0x11e00
	s_addc_u32 s77, s77, 0
	s_waitcnt lgkmcnt(4)
	v_cndmask_b32_e64 v140, v220, v212, s[8:9]
	v_cndmask_b32_e64 v141, v221, v213, s[8:9]
	v_cndmask_b32_e64 v142, v222, v214, s[8:9]
	v_cndmask_b32_e64 v143, v223, v215, s[8:9]
	v_pk_fma_f32 v[164:165], v[238:239], v[140:141], v[250:251] op_sel_hi:[0,1,0]
	v_pk_fma_f32 v[168:169], v[244:245], v[142:143], v[252:253] op_sel_hi:[0,1,0]
	v_pk_fma_f32 v[166:167], v[238:239], v[0:1], v[250:251] op_sel_hi:[0,1,0]
	v_pk_fma_f32 v[170:171], v[244:245], v[4:5], v[252:253] op_sel_hi:[0,1,0]
	v_pk_fma_f32 v[164:165], v[242:243], v[0:1], v[164:165] op_sel_hi:[0,1,1]
	v_pk_fma_f32 v[168:169], v[248:249], v[4:5], v[168:169] op_sel_hi:[0,1,1]
	v_pk_fma_f32 v[166:167], v[242:243], v[2:3], v[166:167] op_sel_hi:[0,1,1]
	v_pk_fma_f32 v[170:171], v[248:249], v[6:7], v[170:171] op_sel_hi:[0,1,1]
	v_fmac_f32_e32 v164, v240, v141
	v_fmac_f32_e32 v168, v246, v143
	v_fmac_f32_e32 v165, v240, v0
	v_fmac_f32_e32 v169, v246, v4
	v_fmac_f32_e32 v166, v240, v1
	v_fmac_f32_e32 v170, v246, v5
	v_fmac_f32_e32 v167, v240, v2
	v_fmac_f32_e32 v171, v246, v6
	v_exp_f32_e32 v144, v164
	v_exp_f32_e32 v145, v165
	v_exp_f32_e32 v146, v166
	v_exp_f32_e32 v147, v167
	v_pk_mul_f32 v[164:165], v[164:165], v[168:169]
	v_pk_mul_f32 v[166:167], v[166:167], v[170:171]
	v_pk_add_f32 v[144:145], v[144:145], v[162:163]
	v_pk_add_f32 v[146:147], v[146:147], v[162:163]
	v_rcp_f32_e32 v144, v144
	v_rcp_f32_e32 v145, v145
	v_rcp_f32_e32 v146, v146
	v_rcp_f32_e64 v147, v147
	s_waitcnt lgkmcnt(0)
	v_cndmask_b32_e64 v140, v224, v216, s[8:9]
	v_cndmask_b32_e64 v141, v225, v217, s[8:9]
	v_cndmask_b32_e64 v142, v226, v218, s[8:9]
	v_cndmask_b32_e64 v143, v227, v219, s[8:9]
	v_pk_fma_f32 v[182:183], v[238:239], v[140:141], v[250:251] op_sel:[1,0,1] op_sel_hi:[1,1,1]
	v_pk_fma_f32 v[186:187], v[244:245], v[142:143], v[252:253] op_sel:[1,0,1] op_sel_hi:[1,1,1]
	v_pk_fma_f32 v[184:185], v[238:239], v[12:13], v[250:251] op_sel:[1,0,1] op_sel_hi:[1,1,1]
	v_pk_fma_f32 v[188:189], v[244:245], v[8:9], v[252:253] op_sel:[1,0,1] op_sel_hi:[1,1,1]
	v_pk_fma_f32 v[182:183], v[242:243], v[12:13], v[182:183] op_sel:[1,0,0] op_sel_hi:[1,1,1]
	v_pk_fma_f32 v[186:187], v[248:249], v[8:9], v[186:187] op_sel:[1,0,0] op_sel_hi:[1,1,1]
	v_pk_fma_f32 v[184:185], v[242:243], v[14:15], v[184:185] op_sel:[1,0,0] op_sel_hi:[1,1,1]
	v_pk_fma_f32 v[188:189], v[248:249], v[10:11], v[188:189] op_sel:[1,0,0] op_sel_hi:[1,1,1]
	v_fmac_f32_e32 v182, v241, v141
	v_fmac_f32_e32 v186, v247, v143
	v_fmac_f32_e32 v183, v241, v12
	v_fmac_f32_e32 v187, v247, v8
	v_fmac_f32_e32 v184, v241, v13
	v_fmac_f32_e32 v188, v247, v9
	v_fmac_f32_e32 v185, v241, v14
	v_fmac_f32_e32 v189, v247, v10
	v_exp_f32_e32 v148, v182
	v_exp_f32_e32 v149, v183
	v_exp_f32_e32 v150, v184
	v_exp_f32_e32 v151, v185
	v_pk_mul_f32 v[182:183], v[182:183], v[186:187]
	v_pk_mul_f32 v[184:185], v[184:185], v[188:189]
	v_pk_add_f32 v[148:149], v[148:149], v[162:163]
	v_pk_add_f32 v[150:151], v[150:151], v[162:163]
	v_rcp_f32_e32 v148, v148
	v_rcp_f32_e32 v149, v149
	v_rcp_f32_e32 v150, v150
	v_rcp_f32_e32 v151, v151
	v_pk_mul_f32 v[164:165], v[164:165], v[144:145]
	v_pk_mul_f32 v[166:167], v[166:167], v[146:147]
	v_pk_mul_f32 v[182:183], v[182:183], v[148:149]
	v_pk_mul_f32 v[184:185], v[184:185], v[150:151]
	v_cvt_pk_bf16_f32 v152, v164, v182
	v_cvt_pk_bf16_f32 v153, v165, v183
	v_cvt_pk_bf16_f32 v154, v166, v184
	v_cvt_pk_bf16_f32 v155, v167, v185
	global_store_dword v157, v152, s[76:77]
	s_add_u32 s76, s76, 0x1600
	s_nop 0
	s_addc_u32 s77, s77, 0
	global_store_dword v157, v153, s[76:77]
	s_add_u32 s76, s76, 0x1600
	s_nop 0
	s_addc_u32 s77, s77, 0
	global_store_dword v157, v154, s[76:77]
	s_add_u32 s76, s76, 0x1600
	s_nop 0
	s_addc_u32 s77, s77, 0
	global_store_dword v157, v155, s[76:77]
	s_andn2_b64 vcc, exec, s[14:15]
	s_mov_b64 s[14:15], -1
	s_cbranch_vccnz .LBB0_882
	s_andn2_b64 vcc, exec, s[38:39]
	s_cbranch_vccnz .LBB0_881
	s_barrier
	s_branch .LBB0_881

; template <class Epi, class Sched, bool ALIGN_EPI = false, bool SP2 = false>
; __device__ __forceinline__ void gemm_phase(PG8_LAS unsigned char* lds, const Gemm g, const Sched& S, const Epi& E) {
;     ...
; #pragma unroll
;         for (int a = 0; a < 2; ++a)
; #pragma unroll
;             for (int b = 0; b < 2; ++b)
; #pragma unroll
;                 for (int m = 0; m < 4; ++m)
; #pragma unroll
;                     for (int n = 0; n < 2; ++n) acc[a][b][m][n] = (f32x4){0.f, 0.f, 0.f, 0.f};
;         cur = nxt; cA = nA; cB = nB; ++ui;
.LBB0_1045:
	s_add_u32 s66, s42, 0x100
	v_mov_b32_e32 v0, 0
	s_addc_u32 s67, s43, 0
	s_mov_b32 s68, -2
	v_mov_b32_e32 v1, v0
	v_mov_b32_e32 v2, v0
	v_mov_b32_e32 v3, v0
	v_mov_b32_e32 v4, v0
	v_mov_b32_e32 v5, v0
	v_mov_b32_e32 v6, v0
	v_mov_b32_e32 v7, v0
	v_mov_b32_e32 v8, v0
	v_mov_b32_e32 v9, v0
	v_mov_b32_e32 v10, v0
	v_mov_b32_e32 v11, v0
	v_mov_b32_e32 v16, v0
	v_mov_b32_e32 v17, v0
	v_mov_b32_e32 v18, v0
	v_mov_b32_e32 v19, v0
	v_mov_b32_e32 v24, v0
	v_mov_b32_e32 v25, v0
	v_mov_b32_e32 v26, v0
	v_mov_b32_e32 v27, v0
	v_mov_b32_e32 v32, v0
	v_mov_b32_e32 v33, v0
	v_mov_b32_e32 v34, v0
	v_mov_b32_e32 v35, v0
	v_mov_b32_e32 v40, v0
	v_mov_b32_e32 v41, v0
	v_mov_b32_e32 v42, v0
	v_mov_b32_e32 v43, v0
	v_mov_b32_e32 v48, v0
	v_mov_b32_e32 v49, v0
	v_mov_b32_e32 v50, v0
	v_mov_b32_e32 v51, v0
	v_mov_b32_e32 v12, v0
	v_mov_b32_e32 v13, v0
	v_mov_b32_e32 v14, v0
	v_mov_b32_e32 v15, v0
	v_mov_b32_e32 v20, v0
	v_mov_b32_e32 v21, v0
	v_mov_b32_e32 v22, v0
	v_mov_b32_e32 v23, v0
	v_mov_b32_e32 v28, v0
	v_mov_b32_e32 v29, v0
	v_mov_b32_e32 v30, v0
	v_mov_b32_e32 v31, v0
	v_mov_b32_e32 v36, v0
	v_mov_b32_e32 v37, v0
	v_mov_b32_e32 v38, v0
	v_mov_b32_e32 v39, v0
	v_mov_b32_e32 v44, v0
	v_mov_b32_e32 v45, v0
	v_mov_b32_e32 v46, v0
	v_mov_b32_e32 v47, v0
	v_mov_b32_e32 v52, v0
	v_mov_b32_e32 v53, v0
	v_mov_b32_e32 v54, v0
	v_mov_b32_e32 v55, v0
	v_mov_b32_e32 v56, v0
	v_mov_b32_e32 v57, v0
	v_mov_b32_e32 v58, v0
	v_mov_b32_e32 v59, v0
	v_mov_b32_e32 v60, v0
	v_mov_b32_e32 v61, v0
	v_mov_b32_e32 v62, v0
	v_mov_b32_e32 v63, v0
	v_mov_b32_e32 v64, v0
	v_mov_b32_e32 v65, v0
	v_mov_b32_e32 v66, v0
	v_mov_b32_e32 v67, v0
	v_mov_b32_e32 v68, v0
	v_mov_b32_e32 v69, v0
	v_mov_b32_e32 v70, v0
	v_mov_b32_e32 v71, v0
	v_mov_b32_e32 v72, v0
	v_mov_b32_e32 v73, v0
	v_mov_b32_e32 v74, v0
	v_mov_b32_e32 v75, v0
	v_mov_b32_e32 v80, v0
	v_mov_b32_e32 v81, v0
	v_mov_b32_e32 v82, v0
	v_mov_b32_e32 v83, v0
	v_mov_b32_e32 v88, v0
	v_mov_b32_e32 v89, v0
	v_mov_b32_e32 v90, v0
	v_mov_b32_e32 v91, v0
	v_mov_b32_e32 v96, v0
	v_mov_b32_e32 v97, v0
	v_mov_b32_e32 v98, v0
	v_mov_b32_e32 v99, v0
	v_mov_b32_e32 v104, v0
	v_mov_b32_e32 v105, v0
	v_mov_b32_e32 v106, v0
	v_mov_b32_e32 v107, v0
	v_mov_b32_e32 v112, v0
	v_mov_b32_e32 v113, v0
	v_mov_b32_e32 v114, v0
	v_mov_b32_e32 v115, v0
	v_mov_b32_e32 v76, v0
	v_mov_b32_e32 v77, v0
	v_mov_b32_e32 v78, v0
	v_mov_b32_e32 v79, v0
	v_mov_b32_e32 v84, v0
	v_mov_b32_e32 v85, v0
	v_mov_b32_e32 v86, v0
	v_mov_b32_e32 v87, v0
	v_mov_b32_e32 v92, v0
	v_mov_b32_e32 v93, v0
	v_mov_b32_e32 v94, v0
	v_mov_b32_e32 v95, v0
	v_mov_b32_e32 v100, v0
	v_mov_b32_e32 v101, v0
	v_mov_b32_e32 v102, v0
	v_mov_b32_e32 v103, v0
	v_mov_b32_e32 v108, v0
	v_mov_b32_e32 v109, v0
	v_mov_b32_e32 v110, v0
	v_mov_b32_e32 v111, v0
	v_mov_b32_e32 v116, v0
	v_mov_b32_e32 v117, v0
	v_mov_b32_e32 v118, v0
	v_mov_b32_e32 v119, v0
	v_mov_b32_e32 v120, v0
	v_mov_b32_e32 v121, v0
	v_mov_b32_e32 v122, v0
	v_mov_b32_e32 v123, v0
	v_mov_b32_e32 v124, v0
	v_mov_b32_e32 v125, v0
	v_mov_b32_e32 v126, v0
	v_mov_b32_e32 v127, v0
	s_nop 0
	s_nop 0
	s_nop 0

; #define PG8_LAS __attribute__((address_space(3)))
;     __device__ __forceinline__ void fused(f32x4 (&acc)[2][2][4][2], const Unit& u, int wr, int wc, int fr, int fq, PG8_LAS unsigned char* lds, int wid, int lane) const {
;         const PG8_LAS float* S = (const PG8_LAS float*)(lds + 4096);
;         const int col0 = u.pn * BM + wc * 32 + 4 * fq;
;         st.run(acc, u, wr, wc, fr, fq, lds, wid, lane);
;         f32x4 g[2][2];
; #pragma unroll
;         for (int bj = 0; bj < 2; ++bj)
; #pragma unroll
;             for (int n = 0; n < 2; ++n) g[bj][n] = *(const f32x4*)(gv + col0 + bj * HALF + n * 16);
; #pragma unroll
;         for (int ai = 0; ai < 2; ++ai)
; #pragma unroll
;             for (int m = 0; m < 4; ++m) { const int r = ai * HALF + wr * 64 + m * 16 + fr; const float rs = S[r]; const size_t off = (size_t)(row_off + u.pm * BM + r) * DM + col0;
; #pragma unroll
;                 for (int bj = 0; bj < 2; ++bj)
; #pragma unroll
;                     for (int n = 0; n < 2; ++n) { const f32x4 bs = *(const f32x4*)(base + off + bj * HALF + n * 16); __builtin_nontemporal_store(bs + acc[ai][bj][m][n] * rs * g[bj][n], (f32x4*)(out + off + bj * HALF + n * 16)); }
;                 if (m & 1) asm volatile("" ::: "memory"); }
;         asm volatile("s_waitcnt lgkmcnt(0)" ::: "memory"); __builtin_amdgcn_s_barrier(); asm volatile("" ::: "memory");
;     }
.LBB0_1113:
	s_or_b64 exec, exec, s[10:11]
	s_lshl_b32 s6, s50, 12
	s_add_i32 s6, s51, s6
	s_ashr_i32 s7, s6, 31
	s_lshl_b64 s[6:7], s[6:7], 2
	s_add_u32 s6, s14, s6
	s_addc_u32 s7, s15, s7
	s_lshl_b32 s9, s16, 5
	s_lshl_b32 s10, s24, 8
	v_lshrrev_b32_e64 v128, 2, v138
	s_or_b32 s9, s10, s9
	v_and_or_b32 v128, v128, 12, s9
	s_waitcnt lgkmcnt(0)
	v_ashrrev_i32_e32 v129, 31, v128
	v_lshlrev_b64 v[150:151], 2, v[128:129]
	s_nop 0
	s_lshl_b32 s8, s50, 14
	v_lshl_add_u64 v[128:129], s[6:7], 0, v[150:151]
	s_lshl_b32 s6, s53, 8
	s_add_i32 s6, s6, s8
	v_add_u32_e32 v152, s6, v157
	v_ashrrev_i32_e32 v153, 31, v152
	v_lshl_add_u64 v[140:141], v[128:129], 0, s[22:23]
	s_nop 0
	v_add_co_u32_e32 v128, vcc, s49, v128
	v_lshlrev_b64 v[132:133], 12, v[152:153]
	v_add_u32_e32 v174, 16, v152
	s_waitcnt lgkmcnt(0)
	s_barrier
	s_mov_b32 s7, 0
	s_lshl_b64 s[6:7], s[6:7], 12
	s_add_u32 s6, s12, s6
	s_addc_u32 s7, s13, s7
	v_and_b32_e32 v136, 8, v157
	v_sub_u32_e32 v157, v157, v136
	v_lshlrev_b32_e32 v137, 3, v136
	v_lshl_add_u32 v144, v157, 2, 0
	v_add_u32_e32 v144, 0x1000, v144
	v_lshl_add_u32 v157, v157, 12, v150
	v_add_u32_e32 v157, v157, v137
	v_add_co_u32_e32 v140, vcc, v137, v140
	s_nop 1
	v_addc_co_u32_e32 v141, vcc, 0, v141, vcc
	global_load_dwordx4 v[128:131], v[140:141], off
	global_load_dwordx4 v[132:135], v[140:141], off offset:512
	ds_read2_b32 v[228:229], v144 offset0:0 offset1:8
	ds_read2_b32 v[230:231], v144 offset0:16 offset1:24
	ds_read2_b32 v[232:233], v144 offset0:32 offset1:40
	ds_read2_b32 v[234:235], v144 offset0:48 offset1:56
	ds_read2_b32 v[236:237], v144 offset0:128 offset1:136
	ds_read2_b32 v[238:239], v144 offset0:144 offset1:152
	ds_read2_b32 v[240:241], v144 offset0:160 offset1:168
	ds_read2_b32 v[242:243], v144 offset0:176 offset1:184
	v_mov_b32_e64 v252, v157
	v_add_u32_e32 v253, 0x8000, v157
	global_load_dwordx4 v[158:161], v252, s[6:7] nt
	global_load_dwordx4 v[162:165], v253, s[6:7] nt
	v_mov_b32_e64 v252, v157
	v_add_u32_e32 v253, 0x8000, v157
	global_load_dwordx4 v[166:169], v252, s[6:7] offset:512 nt
	global_load_dwordx4 v[170:173], v253, s[6:7] offset:512 nt
	v_add_u32_e32 v252, 0x10000, v157
	v_add_u32_e32 v253, 0x18000, v157
	global_load_dwordx4 v[174:177], v252, s[6:7] nt
	global_load_dwordx4 v[178:181], v253, s[6:7] nt
	v_add_u32_e32 v252, 0x10000, v157
	v_add_u32_e32 v253, 0x18000, v157
	global_load_dwordx4 v[182:185], v252, s[6:7] offset:512 nt
	global_load_dwordx4 v[186:189], v253, s[6:7] offset:512 nt
	v_add_u32_e32 v252, 0x20000, v157
	v_add_u32_e32 v253, 0x28000, v157
	global_load_dwordx4 v[196:199], v252, s[6:7] nt
	global_load_dwordx4 v[200:203], v253, s[6:7] nt
	v_add_u32_e32 v252, 0x20000, v157
	v_add_u32_e32 v253, 0x28000, v157
	global_load_dwordx4 v[204:207], v252, s[6:7] offset:512 nt
	global_load_dwordx4 v[208:211], v253, s[6:7] offset:512 nt
	v_add_u32_e32 v252, 0x30000, v157
	v_add_u32_e32 v253, 0x38000, v157
	global_load_dwordx4 v[212:215], v252, s[6:7] nt
	global_load_dwordx4 v[216:219], v253, s[6:7] nt
	v_add_u32_e32 v252, 0x30000, v157
	v_add_u32_e32 v253, 0x38000, v157
	global_load_dwordx4 v[220:223], v252, s[6:7] offset:512 nt
	global_load_dwordx4 v[224:227], v253, s[6:7] offset:512 nt
	s_waitcnt lgkmcnt(0)
	v_mov_b32_e32 v190, v124
	v_mov_b32_e32 v191, v125
	v_mov_b32_e32 v192, v126
	v_mov_b32_e64 v193, v127
	v_mov_b32_dpp v124, v120 row_ror:8 row_mask:0xf bank_mask:0xc
	v_mov_b32_dpp v125, v121 row_ror:8 row_mask:0xf bank_mask:0xc
	v_mov_b32_dpp v126, v122 row_ror:8 row_mask:0xf bank_mask:0xc
	v_mov_b32_dpp v127, v123 row_ror:8 row_mask:0xf bank_mask:0xc
	v_mov_b32_dpp v120, v190 row_ror:8 row_mask:0xf bank_mask:0x3
	v_mov_b32_dpp v121, v191 row_ror:8 row_mask:0xf bank_mask:0x3
	v_mov_b32_dpp v122, v192 row_ror:8 row_mask:0xf bank_mask:0x3
	v_mov_b32_dpp v123, v193 row_ror:8 row_mask:0xf bank_mask:0x3
	s_waitcnt vmcnt(14)
	v_mul_f32_e32 v124, v124, v228
	v_mul_f32_e32 v125, v125, v228
	v_mul_f32_e32 v126, v126, v228
	v_mul_f32_e32 v127, v127, v228
	v_mul_f32_e32 v120, v120, v229
	v_mul_f32_e32 v121, v121, v229
	v_mul_f32_e32 v122, v122, v229
	v_mul_f32_e64 v123, v123, v229
	v_fma_f32 v124, v124, v128, v158
	v_fma_f32 v125, v125, v129, v159
	v_fma_f32 v126, v126, v130, v160
	v_fma_f32 v127, v127, v131, v161
	v_fma_f32 v120, v120, v128, v162
	v_fma_f32 v121, v121, v129, v163
	v_fma_f32 v122, v122, v130, v164
	v_fma_f32 v123, v123, v131, v165
	v_mov_b32_e64 v252, v157
	v_add_u32_e32 v253, 0x8000, v157
	global_store_dwordx4 v252, v[124:127], s[6:7] nt
	global_store_dwordx4 v253, v[120:123], s[6:7] nt
	v_add_u32_e32 v252, 0x80000, v157
	v_add_u32_e32 v253, 0x88000, v157
	global_load_dwordx4 v[158:161], v252, s[6:7] nt
	global_load_dwordx4 v[162:165], v253, s[6:7] nt
	v_mov_b32_e32 v190, v108
	v_mov_b32_e32 v191, v109
	v_mov_b32_e32 v192, v110
	v_mov_b32_e32 v193, v111
	v_mov_b32_dpp v108, v104 row_ror:8 row_mask:0xf bank_mask:0xc
	v_mov_b32_dpp v109, v105 row_ror:8 row_mask:0xf bank_mask:0xc
	v_mov_b32_dpp v110, v106 row_ror:8 row_mask:0xf bank_mask:0xc
	v_mov_b32_dpp v111, v107 row_ror:8 row_mask:0xf bank_mask:0xc
	v_mov_b32_dpp v104, v190 row_ror:8 row_mask:0xf bank_mask:0x3
	v_mov_b32_dpp v105, v191 row_ror:8 row_mask:0xf bank_mask:0x3
	v_mov_b32_dpp v106, v192 row_ror:8 row_mask:0xf bank_mask:0x3
	v_mov_b32_dpp v107, v193 row_ror:8 row_mask:0xf bank_mask:0x3
	s_waitcnt vmcnt(16)
;     __device__ __forceinline__ void fused(f32x4 (&acc)[2][2][4][2], const Unit& u, int wr, int wc, int fr, int fq, PG8_LAS unsigned char* lds, int wid, int lane) const {
;     ...
; #pragma unroll
;         for (int ai = 0; ai < 2; ++ai)
; #pragma unroll
;             for (int m = 0; m < 4; ++m) { const int r = ai * HALF + wr * 64 + m * 16 + fr; const float rs = S[r]; const size_t off = (size_t)(row_off + u.pm * BM + r) * DM + col0;
; #pragma unroll
;                 for (int bj = 0; bj < 2; ++bj)
; #pragma unroll
;                     for (int n = 0; n < 2; ++n) { const f32x4 bs = *(const f32x4*)(base + off + bj * HALF + n * 16); __builtin_nontemporal_store(bs + acc[ai][bj][m][n] * rs * g[bj][n], (f32x4*)(out + off + bj * HALF + n * 16)); }
;                 if (m & 1) asm volatile("" ::: "memory"); }
	v_mul_f32_e32 v108, v108, v228
	v_mul_f32_e32 v109, v109, v228
	v_mul_f32_e32 v110, v110, v228
	v_mul_f32_e32 v111, v111, v228
	v_mul_f32_e32 v104, v104, v229
	v_mul_f32_e32 v105, v105, v229
	v_mul_f32_e32 v106, v106, v229
	v_mul_f32_e64 v107, v107, v229
	v_fma_f32 v108, v108, v132, v166
	v_fma_f32 v109, v109, v133, v167
	v_fma_f32 v110, v110, v134, v168
	v_fma_f32 v111, v111, v135, v169
	v_fma_f32 v104, v104, v132, v170
	v_fma_f32 v105, v105, v133, v171
	v_fma_f32 v106, v106, v134, v172
	v_fma_f32 v107, v107, v135, v173
	v_mov_b32_e64 v252, v157
	v_add_u32_e32 v253, 0x8000, v157
	global_store_dwordx4 v252, v[108:111], s[6:7] offset:512 nt
	global_store_dwordx4 v253, v[104:107], s[6:7] offset:512 nt
	v_add_u32_e32 v252, 0x80000, v157
	v_add_u32_e32 v253, 0x88000, v157
	global_load_dwordx4 v[166:169], v252, s[6:7] offset:512 nt
	global_load_dwordx4 v[170:173], v253, s[6:7] offset:512 nt
	v_mov_b32_e32 v190, v116
	v_mov_b32_e32 v191, v117
	v_mov_b32_e32 v192, v118
	v_mov_b32_e32 v193, v119
	v_mov_b32_dpp v116, v112 row_ror:8 row_mask:0xf bank_mask:0xc
	v_mov_b32_dpp v117, v113 row_ror:8 row_mask:0xf bank_mask:0xc
	v_mov_b32_dpp v118, v114 row_ror:8 row_mask:0xf bank_mask:0xc
	v_mov_b32_dpp v119, v115 row_ror:8 row_mask:0xf bank_mask:0xc
	v_mov_b32_dpp v112, v190 row_ror:8 row_mask:0xf bank_mask:0x3
	v_mov_b32_dpp v113, v191 row_ror:8 row_mask:0xf bank_mask:0x3
	v_mov_b32_dpp v114, v192 row_ror:8 row_mask:0xf bank_mask:0x3
	v_mov_b32_dpp v115, v193 row_ror:8 row_mask:0xf bank_mask:0x3
	s_waitcnt vmcnt(18)
	v_mul_f32_e32 v116, v116, v230
	v_mul_f32_e32 v117, v117, v230
	v_mul_f32_e32 v118, v118, v230
	v_mul_f32_e32 v119, v119, v230
	v_mul_f32_e32 v112, v112, v231
	v_mul_f32_e32 v113, v113, v231
	v_mul_f32_e32 v114, v114, v231
	v_mul_f32_e64 v115, v115, v231
	v_fma_f32 v116, v116, v128, v174
	v_fma_f32 v117, v117, v129, v175
	v_fma_f32 v118, v118, v130, v176
	v_fma_f32 v119, v119, v131, v177
	v_fma_f32 v112, v112, v128, v178
	v_fma_f32 v113, v113, v129, v179
	v_fma_f32 v114, v114, v130, v180
	v_fma_f32 v115, v115, v131, v181
	v_add_u32_e32 v252, 0x10000, v157
	v_add_u32_e32 v253, 0x18000, v157
	global_store_dwordx4 v252, v[116:119], s[6:7] nt
	global_store_dwordx4 v253, v[112:115], s[6:7] nt
	v_add_u32_e32 v252, 0x90000, v157
	v_add_u32_e32 v253, 0x98000, v157
	global_load_dwordx4 v[174:177], v252, s[6:7] nt
	global_load_dwordx4 v[178:181], v253, s[6:7] nt
	v_mov_b32_e32 v190, v100
	v_mov_b32_e32 v191, v101
	v_mov_b32_e32 v192, v102
	v_mov_b32_e32 v193, v103
	v_mov_b32_dpp v100, v96 row_ror:8 row_mask:0xf bank_mask:0xc
	v_mov_b32_dpp v101, v97 row_ror:8 row_mask:0xf bank_mask:0xc
	v_mov_b32_dpp v102, v98 row_ror:8 row_mask:0xf bank_mask:0xc
	v_mov_b32_dpp v103, v99 row_ror:8 row_mask:0xf bank_mask:0xc
	v_mov_b32_dpp v96, v190 row_ror:8 row_mask:0xf bank_mask:0x3
	v_mov_b32_dpp v97, v191 row_ror:8 row_mask:0xf bank_mask:0x3
	v_mov_b32_dpp v98, v192 row_ror:8 row_mask:0xf bank_mask:0x3
	v_mov_b32_dpp v99, v193 row_ror:8 row_mask:0xf bank_mask:0x3
	s_waitcnt vmcnt(20)
	v_mul_f32_e32 v100, v100, v230
	v_mul_f32_e32 v101, v101, v230
	v_mul_f32_e32 v102, v102, v230
	v_mul_f32_e32 v103, v103, v230
	v_mul_f32_e32 v96, v96, v231
	v_mul_f32_e32 v97, v97, v231
	v_mul_f32_e32 v98, v98, v231
	v_mul_f32_e64 v99, v99, v231
	v_fma_f32 v100, v100, v132, v182
	v_fma_f32 v101, v101, v133, v183
	v_fma_f32 v102, v102, v134, v184
	v_fma_f32 v103, v103, v135, v185
	v_fma_f32 v96, v96, v132, v186
	v_fma_f32 v97, v97, v133, v187
	v_fma_f32 v98, v98, v134, v188
	v_fma_f32 v99, v99, v135, v189
	v_add_u32_e32 v252, 0x10000, v157
	v_add_u32_e32 v253, 0x18000, v157
	global_store_dwordx4 v252, v[100:103], s[6:7] offset:512 nt
	global_store_dwordx4 v253, v[96:99], s[6:7] offset:512 nt
	v_add_u32_e32 v252, 0x90000, v157
	v_add_u32_e32 v253, 0x98000, v157
	global_load_dwordx4 v[182:185], v252, s[6:7] offset:512 nt
	global_load_dwordx4 v[186:189], v253, s[6:7] offset:512 nt
	v_mov_b32_e32 v190, v92
	v_mov_b32_e32 v191, v93
	v_mov_b32_e32 v192, v94
	v_mov_b32_e32 v193, v95
	v_mov_b32_dpp v92, v88 row_ror:8 row_mask:0xf bank_mask:0xc
	v_mov_b32_dpp v93, v89 row_ror:8 row_mask:0xf bank_mask:0xc
	v_mov_b32_dpp v94, v90 row_ror:8 row_mask:0xf bank_mask:0xc
	v_mov_b32_dpp v95, v91 row_ror:8 row_mask:0xf bank_mask:0xc
	v_mov_b32_dpp v88, v190 row_ror:8 row_mask:0xf bank_mask:0x3
	v_mov_b32_dpp v89, v191 row_ror:8 row_mask:0xf bank_mask:0x3
	v_mov_b32_dpp v90, v192 row_ror:8 row_mask:0xf bank_mask:0x3
	v_mov_b32_dpp v91, v193 row_ror:8 row_mask:0xf bank_mask:0x3
	s_waitcnt vmcnt(22)
	v_mul_f32_e32 v92, v92, v232
	v_mul_f32_e32 v93, v93, v232
	v_mul_f32_e32 v94, v94, v232
	v_mul_f32_e32 v95, v95, v232
	v_mul_f32_e32 v88, v88, v233
	v_mul_f32_e32 v89, v89, v233
	v_mul_f32_e32 v90, v90, v233
	v_mul_f32_e64 v91, v91, v233
	v_fma_f32 v92, v92, v128, v196
	v_fma_f32 v93, v93, v129, v197
	v_fma_f32 v94, v94, v130, v198
	v_fma_f32 v95, v95, v131, v199
	v_fma_f32 v88, v88, v128, v200
	v_fma_f32 v89, v89, v129, v201
	v_fma_f32 v90, v90, v130, v202
	v_fma_f32 v91, v91, v131, v203
	v_add_u32_e32 v252, 0x20000, v157
	v_add_u32_e32 v253, 0x28000, v157
	global_store_dwordx4 v252, v[92:95], s[6:7] nt
	global_store_dwordx4 v253, v[88:91], s[6:7] nt
	v_add_u32_e32 v252, 0xa0000, v157
	v_add_u32_e32 v253, 0xa8000, v157
	global_load_dwordx4 v[196:199], v252, s[6:7] nt
	global_load_dwordx4 v[200:203], v253, s[6:7] nt
	v_mov_b32_e32 v190, v76
	v_mov_b32_e32 v191, v77
	v_mov_b32_e32 v192, v78
	v_mov_b32_e32 v193, v79
	v_mov_b32_dpp v76, v72 row_ror:8 row_mask:0xf bank_mask:0xc
	v_mov_b32_dpp v77, v73 row_ror:8 row_mask:0xf bank_mask:0xc
	v_mov_b32_dpp v78, v74 row_ror:8 row_mask:0xf bank_mask:0xc
	v_mov_b32_dpp v79, v75 row_ror:8 row_mask:0xf bank_mask:0xc
	v_mov_b32_dpp v72, v190 row_ror:8 row_mask:0xf bank_mask:0x3
	v_mov_b32_dpp v73, v191 row_ror:8 row_mask:0xf bank_mask:0x3
	v_mov_b32_dpp v74, v192 row_ror:8 row_mask:0xf bank_mask:0x3
	v_mov_b32_dpp v75, v193 row_ror:8 row_mask:0xf bank_mask:0x3
	s_waitcnt vmcnt(24)
;     __device__ __forceinline__ void fused(f32x4 (&acc)[2][2][4][2], const Unit& u, int wr, int wc, int fr, int fq, PG8_LAS unsigned char* lds, int wid, int lane) const {
;     ...
; #pragma unroll
;         for (int ai = 0; ai < 2; ++ai)
; #pragma unroll
;             for (int m = 0; m < 4; ++m) { const int r = ai * HALF + wr * 64 + m * 16 + fr; const float rs = S[r]; const size_t off = (size_t)(row_off + u.pm * BM + r) * DM + col0;
; #pragma unroll
;                 for (int bj = 0; bj < 2; ++bj)
; #pragma unroll
;                     for (int n = 0; n < 2; ++n) { const f32x4 bs = *(const f32x4*)(base + off + bj * HALF + n * 16); __builtin_nontemporal_store(bs + acc[ai][bj][m][n] * rs * g[bj][n], (f32x4*)(out + off + bj * HALF + n * 16)); }
;                 if (m & 1) asm volatile("" ::: "memory"); }
	v_mul_f32_e32 v76, v76, v232
	v_mul_f32_e32 v77, v77, v232
	v_mul_f32_e32 v78, v78, v232
	v_mul_f32_e32 v79, v79, v232
	v_mul_f32_e32 v72, v72, v233
	v_mul_f32_e32 v73, v73, v233
	v_mul_f32_e32 v74, v74, v233
	v_mul_f32_e64 v75, v75, v233
	v_fma_f32 v76, v76, v132, v204
	v_fma_f32 v77, v77, v133, v205
	v_fma_f32 v78, v78, v134, v206
	v_fma_f32 v79, v79, v135, v207
	v_fma_f32 v72, v72, v132, v208
	v_fma_f32 v73, v73, v133, v209
	v_fma_f32 v74, v74, v134, v210
	v_fma_f32 v75, v75, v135, v211
	v_add_u32_e32 v252, 0x20000, v157
	v_add_u32_e32 v253, 0x28000, v157
	global_store_dwordx4 v252, v[76:79], s[6:7] offset:512 nt
	global_store_dwordx4 v253, v[72:75], s[6:7] offset:512 nt
	v_add_u32_e32 v252, 0xa0000, v157
	v_add_u32_e32 v253, 0xa8000, v157
	global_load_dwordx4 v[204:207], v252, s[6:7] offset:512 nt
	global_load_dwordx4 v[208:211], v253, s[6:7] offset:512 nt
	v_mov_b32_e32 v190, v84
	v_mov_b32_e32 v191, v85
	v_mov_b32_e32 v192, v86
	v_mov_b32_e32 v193, v87
	v_mov_b32_dpp v84, v80 row_ror:8 row_mask:0xf bank_mask:0xc
	v_mov_b32_dpp v85, v81 row_ror:8 row_mask:0xf bank_mask:0xc
	v_mov_b32_dpp v86, v82 row_ror:8 row_mask:0xf bank_mask:0xc
	v_mov_b32_dpp v87, v83 row_ror:8 row_mask:0xf bank_mask:0xc
	v_mov_b32_dpp v80, v190 row_ror:8 row_mask:0xf bank_mask:0x3
	v_mov_b32_dpp v81, v191 row_ror:8 row_mask:0xf bank_mask:0x3
	v_mov_b32_dpp v82, v192 row_ror:8 row_mask:0xf bank_mask:0x3
	v_mov_b32_dpp v83, v193 row_ror:8 row_mask:0xf bank_mask:0x3
	s_waitcnt vmcnt(26)
	v_mul_f32_e32 v84, v84, v234
	v_mul_f32_e32 v85, v85, v234
	v_mul_f32_e32 v86, v86, v234
	v_mul_f32_e32 v87, v87, v234
	v_mul_f32_e32 v80, v80, v235
	v_mul_f32_e32 v81, v81, v235
	v_mul_f32_e32 v82, v82, v235
	v_mul_f32_e64 v83, v83, v235
	v_fma_f32 v84, v84, v128, v212
	v_fma_f32 v85, v85, v129, v213
	v_fma_f32 v86, v86, v130, v214
	v_fma_f32 v87, v87, v131, v215
	v_fma_f32 v80, v80, v128, v216
	v_fma_f32 v81, v81, v129, v217
	v_fma_f32 v82, v82, v130, v218
	v_fma_f32 v83, v83, v131, v219
	v_add_u32_e32 v252, 0x30000, v157
	v_add_u32_e32 v253, 0x38000, v157
	global_store_dwordx4 v252, v[84:87], s[6:7] nt
	global_store_dwordx4 v253, v[80:83], s[6:7] nt
	v_add_u32_e32 v252, 0xb0000, v157
	v_add_u32_e32 v253, 0xb8000, v157
	global_load_dwordx4 v[212:215], v252, s[6:7] nt
	global_load_dwordx4 v[216:219], v253, s[6:7] nt
	v_mov_b32_e32 v190, v68
	v_mov_b32_e32 v191, v69
	v_mov_b32_e32 v192, v70
	v_mov_b32_e32 v193, v71
	v_mov_b32_dpp v68, v64 row_ror:8 row_mask:0xf bank_mask:0xc
	v_mov_b32_dpp v69, v65 row_ror:8 row_mask:0xf bank_mask:0xc
	v_mov_b32_dpp v70, v66 row_ror:8 row_mask:0xf bank_mask:0xc
	v_mov_b32_dpp v71, v67 row_ror:8 row_mask:0xf bank_mask:0xc
	v_mov_b32_dpp v64, v190 row_ror:8 row_mask:0xf bank_mask:0x3
	v_mov_b32_dpp v65, v191 row_ror:8 row_mask:0xf bank_mask:0x3
	v_mov_b32_dpp v66, v192 row_ror:8 row_mask:0xf bank_mask:0x3
	v_mov_b32_dpp v67, v193 row_ror:8 row_mask:0xf bank_mask:0x3
	s_waitcnt vmcnt(28)
	v_mul_f32_e32 v68, v68, v234
	v_mul_f32_e32 v69, v69, v234
	v_mul_f32_e32 v70, v70, v234
	v_mul_f32_e32 v71, v71, v234
	v_mul_f32_e32 v64, v64, v235
	v_mul_f32_e32 v65, v65, v235
	v_mul_f32_e32 v66, v66, v235
	v_mul_f32_e64 v67, v67, v235
	v_fma_f32 v68, v68, v132, v220
	v_fma_f32 v69, v69, v133, v221
	v_fma_f32 v70, v70, v134, v222
	v_fma_f32 v71, v71, v135, v223
	v_fma_f32 v64, v64, v132, v224
	v_fma_f32 v65, v65, v133, v225
	v_fma_f32 v66, v66, v134, v226
	v_fma_f32 v67, v67, v135, v227
	v_add_u32_e32 v252, 0x30000, v157
	v_add_u32_e32 v253, 0x38000, v157
	global_store_dwordx4 v252, v[68:71], s[6:7] offset:512 nt
	global_store_dwordx4 v253, v[64:67], s[6:7] offset:512 nt
	v_add_u32_e32 v252, 0xb0000, v157
	v_add_u32_e32 v253, 0xb8000, v157
	global_load_dwordx4 v[220:223], v252, s[6:7] offset:512 nt
	global_load_dwordx4 v[224:227], v253, s[6:7] offset:512 nt
	v_mov_b32_e32 v190, v60
	v_mov_b32_e32 v191, v61
	v_mov_b32_e32 v192, v62
	v_mov_b32_e32 v193, v63
	v_mov_b32_dpp v60, v56 row_ror:8 row_mask:0xf bank_mask:0xc
	v_mov_b32_dpp v61, v57 row_ror:8 row_mask:0xf bank_mask:0xc
	v_mov_b32_dpp v62, v58 row_ror:8 row_mask:0xf bank_mask:0xc
	v_mov_b32_dpp v63, v59 row_ror:8 row_mask:0xf bank_mask:0xc
	v_mov_b32_dpp v56, v190 row_ror:8 row_mask:0xf bank_mask:0x3
	v_mov_b32_dpp v57, v191 row_ror:8 row_mask:0xf bank_mask:0x3
	v_mov_b32_dpp v58, v192 row_ror:8 row_mask:0xf bank_mask:0x3
	v_mov_b32_dpp v59, v193 row_ror:8 row_mask:0xf bank_mask:0x3
	s_waitcnt vmcnt(28)
	v_mul_f32_e32 v60, v60, v236
	v_mul_f32_e32 v61, v61, v236
	v_mul_f32_e32 v62, v62, v236
	v_mul_f32_e32 v63, v63, v236
	v_mul_f32_e32 v56, v56, v237
	v_mul_f32_e32 v57, v57, v237
	v_mul_f32_e32 v58, v58, v237
	v_mul_f32_e64 v59, v59, v237
	v_fma_f32 v60, v60, v128, v158
	v_fma_f32 v61, v61, v129, v159
	v_fma_f32 v62, v62, v130, v160
	v_fma_f32 v63, v63, v131, v161
	v_fma_f32 v56, v56, v128, v162
	v_fma_f32 v57, v57, v129, v163
	v_fma_f32 v58, v58, v130, v164
	v_fma_f32 v59, v59, v131, v165
	v_add_u32_e32 v252, 0x80000, v157
	v_add_u32_e32 v253, 0x88000, v157
	global_store_dwordx4 v252, v[60:63], s[6:7] nt
	global_store_dwordx4 v253, v[56:59], s[6:7] nt
	v_mov_b32_e32 v190, v44
	v_mov_b32_e32 v191, v45
	v_mov_b32_e32 v192, v46
	v_mov_b32_e32 v193, v47
	v_mov_b32_dpp v44, v40 row_ror:8 row_mask:0xf bank_mask:0xc
	v_mov_b32_dpp v45, v41 row_ror:8 row_mask:0xf bank_mask:0xc
	v_mov_b32_dpp v46, v42 row_ror:8 row_mask:0xf bank_mask:0xc
	v_mov_b32_dpp v47, v43 row_ror:8 row_mask:0xf bank_mask:0xc
	v_mov_b32_dpp v40, v190 row_ror:8 row_mask:0xf bank_mask:0x3
	v_mov_b32_dpp v41, v191 row_ror:8 row_mask:0xf bank_mask:0x3
	v_mov_b32_dpp v42, v192 row_ror:8 row_mask:0xf bank_mask:0x3
	v_mov_b32_dpp v43, v193 row_ror:8 row_mask:0xf bank_mask:0x3
	s_waitcnt vmcnt(26)
;     __device__ __forceinline__ void fused(f32x4 (&acc)[2][2][4][2], const Unit& u, int wr, int wc, int fr, int fq, PG8_LAS unsigned char* lds, int wid, int lane) const {
;     ...
; #pragma unroll
;         for (int ai = 0; ai < 2; ++ai)
; #pragma unroll
;             for (int m = 0; m < 4; ++m) { const int r = ai * HALF + wr * 64 + m * 16 + fr; const float rs = S[r]; const size_t off = (size_t)(row_off + u.pm * BM + r) * DM + col0;
; #pragma unroll
;                 for (int bj = 0; bj < 2; ++bj)
; #pragma unroll
;                     for (int n = 0; n < 2; ++n) { const f32x4 bs = *(const f32x4*)(base + off + bj * HALF + n * 16); __builtin_nontemporal_store(bs + acc[ai][bj][m][n] * rs * g[bj][n], (f32x4*)(out + off + bj * HALF + n * 16)); }
;                 if (m & 1) asm volatile("" ::: "memory"); }
	v_mul_f32_e32 v44, v44, v236
	v_mul_f32_e32 v45, v45, v236
	v_mul_f32_e32 v46, v46, v236
	v_mul_f32_e32 v47, v47, v236
	v_mul_f32_e32 v40, v40, v237
	v_mul_f32_e32 v41, v41, v237
	v_mul_f32_e32 v42, v42, v237
	v_mul_f32_e64 v43, v43, v237
	v_fma_f32 v44, v44, v132, v166
	v_fma_f32 v45, v45, v133, v167
	v_fma_f32 v46, v46, v134, v168
	v_fma_f32 v47, v47, v135, v169
	v_fma_f32 v40, v40, v132, v170
	v_fma_f32 v41, v41, v133, v171
	v_fma_f32 v42, v42, v134, v172
	v_fma_f32 v43, v43, v135, v173
	v_add_u32_e32 v252, 0x80000, v157
	v_add_u32_e32 v253, 0x88000, v157
	global_store_dwordx4 v252, v[44:47], s[6:7] offset:512 nt
	global_store_dwordx4 v253, v[40:43], s[6:7] offset:512 nt
	v_mov_b32_e32 v190, v52
	v_mov_b32_e32 v191, v53
	v_mov_b32_e32 v192, v54
	v_mov_b32_e32 v193, v55
	v_mov_b32_dpp v52, v48 row_ror:8 row_mask:0xf bank_mask:0xc
	v_mov_b32_dpp v53, v49 row_ror:8 row_mask:0xf bank_mask:0xc
	v_mov_b32_dpp v54, v50 row_ror:8 row_mask:0xf bank_mask:0xc
	v_mov_b32_dpp v55, v51 row_ror:8 row_mask:0xf bank_mask:0xc
	v_mov_b32_dpp v48, v190 row_ror:8 row_mask:0xf bank_mask:0x3
	v_mov_b32_dpp v49, v191 row_ror:8 row_mask:0xf bank_mask:0x3
	v_mov_b32_dpp v50, v192 row_ror:8 row_mask:0xf bank_mask:0x3
	v_mov_b32_dpp v51, v193 row_ror:8 row_mask:0xf bank_mask:0x3
	s_waitcnt vmcnt(24)
	v_mul_f32_e32 v52, v52, v238
	v_mul_f32_e32 v53, v53, v238
	v_mul_f32_e32 v54, v54, v238
	v_mul_f32_e32 v55, v55, v238
	v_mul_f32_e32 v48, v48, v239
	v_mul_f32_e32 v49, v49, v239
	v_mul_f32_e32 v50, v50, v239
	v_mul_f32_e64 v51, v51, v239
	v_fma_f32 v52, v52, v128, v174
	v_fma_f32 v53, v53, v129, v175
	v_fma_f32 v54, v54, v130, v176
	v_fma_f32 v55, v55, v131, v177
	v_fma_f32 v48, v48, v128, v178
	v_fma_f32 v49, v49, v129, v179
	v_fma_f32 v50, v50, v130, v180
	v_fma_f32 v51, v51, v131, v181
	v_add_u32_e32 v252, 0x90000, v157
	v_add_u32_e32 v253, 0x98000, v157
	global_store_dwordx4 v252, v[52:55], s[6:7] nt
	global_store_dwordx4 v253, v[48:51], s[6:7] nt
	v_mov_b32_e32 v190, v36
	v_mov_b32_e32 v191, v37
	v_mov_b32_e32 v192, v38
	v_mov_b32_e32 v193, v39
	v_mov_b32_dpp v36, v32 row_ror:8 row_mask:0xf bank_mask:0xc
	v_mov_b32_dpp v37, v33 row_ror:8 row_mask:0xf bank_mask:0xc
	v_mov_b32_dpp v38, v34 row_ror:8 row_mask:0xf bank_mask:0xc
	v_mov_b32_dpp v39, v35 row_ror:8 row_mask:0xf bank_mask:0xc
	v_mov_b32_dpp v32, v190 row_ror:8 row_mask:0xf bank_mask:0x3
	v_mov_b32_dpp v33, v191 row_ror:8 row_mask:0xf bank_mask:0x3
	v_mov_b32_dpp v34, v192 row_ror:8 row_mask:0xf bank_mask:0x3
	v_mov_b32_dpp v35, v193 row_ror:8 row_mask:0xf bank_mask:0x3
	s_waitcnt vmcnt(22)
	v_mul_f32_e32 v36, v36, v238
	v_mul_f32_e32 v37, v37, v238
	v_mul_f32_e32 v38, v38, v238
	v_mul_f32_e32 v39, v39, v238
	v_mul_f32_e32 v32, v32, v239
	v_mul_f32_e32 v33, v33, v239
	v_mul_f32_e32 v34, v34, v239
	v_mul_f32_e64 v35, v35, v239
	v_fma_f32 v36, v36, v132, v182
	v_fma_f32 v37, v37, v133, v183
	v_fma_f32 v38, v38, v134, v184
	v_fma_f32 v39, v39, v135, v185
	v_fma_f32 v32, v32, v132, v186
	v_fma_f32 v33, v33, v133, v187
	v_fma_f32 v34, v34, v134, v188
	v_fma_f32 v35, v35, v135, v189
	v_add_u32_e32 v252, 0x90000, v157
	v_add_u32_e32 v253, 0x98000, v157
	global_store_dwordx4 v252, v[36:39], s[6:7] offset:512 nt
	global_store_dwordx4 v253, v[32:35], s[6:7] offset:512 nt
	v_mov_b32_e32 v190, v28
	v_mov_b32_e32 v191, v29
	v_mov_b32_e32 v192, v30
	v_mov_b32_e32 v193, v31
	v_mov_b32_dpp v28, v24 row_ror:8 row_mask:0xf bank_mask:0xc
	v_mov_b32_dpp v29, v25 row_ror:8 row_mask:0xf bank_mask:0xc
	v_mov_b32_dpp v30, v26 row_ror:8 row_mask:0xf bank_mask:0xc
	v_mov_b32_dpp v31, v27 row_ror:8 row_mask:0xf bank_mask:0xc
	v_mov_b32_dpp v24, v190 row_ror:8 row_mask:0xf bank_mask:0x3
	v_mov_b32_dpp v25, v191 row_ror:8 row_mask:0xf bank_mask:0x3
	v_mov_b32_dpp v26, v192 row_ror:8 row_mask:0xf bank_mask:0x3
	v_mov_b32_dpp v27, v193 row_ror:8 row_mask:0xf bank_mask:0x3
	s_waitcnt vmcnt(20)
;     __device__ __forceinline__ void fused(f32x4 (&acc)[2][2][4][2], const Unit& u, int wr, int wc, int fr, int fq, PG8_LAS unsigned char* lds, int wid, int lane) const {
;     ...
;             for (int m = 0; m < 4; ++m) { const int r = ai * HALF + wr * 64 + m * 16 + fr; const float rs = S[r]; const size_t off = (size_t)(row_off + u.pm * BM + r) * DM + col0;
; #pragma unroll
;                 for (int bj = 0; bj < 2; ++bj)
; #pragma unroll
;                     for (int n = 0; n < 2; ++n) { const f32x4 bs = *(const f32x4*)(base + off + bj * HALF + n * 16); __builtin_nontemporal_store(bs + acc[ai][bj][m][n] * rs * g[bj][n], (f32x4*)(out + off + bj * HALF + n * 16)); }
;                 if (m & 1) asm volatile("" ::: "memory"); }
	v_mul_f32_e32 v28, v28, v240
	v_mul_f32_e32 v29, v29, v240
	v_mul_f32_e32 v30, v30, v240
	v_mul_f32_e32 v31, v31, v240
	v_mul_f32_e32 v24, v24, v241
	v_mul_f32_e32 v25, v25, v241
	v_mul_f32_e32 v26, v26, v241
	v_mul_f32_e64 v27, v27, v241
	v_fma_f32 v28, v28, v128, v196
	v_fma_f32 v29, v29, v129, v197
	v_fma_f32 v30, v30, v130, v198
	v_fma_f32 v31, v31, v131, v199
	v_fma_f32 v24, v24, v128, v200
	v_fma_f32 v25, v25, v129, v201
	v_fma_f32 v26, v26, v130, v202
	v_fma_f32 v27, v27, v131, v203
	v_add_u32_e32 v252, 0xa0000, v157
	v_add_u32_e32 v253, 0xa8000, v157
	global_store_dwordx4 v252, v[28:31], s[6:7] nt
	global_store_dwordx4 v253, v[24:27], s[6:7] nt
	v_mov_b32_e32 v190, v12
	v_mov_b32_e32 v191, v13
	v_mov_b32_e32 v192, v14
	v_mov_b32_e32 v193, v15
	v_mov_b32_dpp v12, v8 row_ror:8 row_mask:0xf bank_mask:0xc
	v_mov_b32_dpp v13, v9 row_ror:8 row_mask:0xf bank_mask:0xc
	v_mov_b32_dpp v14, v10 row_ror:8 row_mask:0xf bank_mask:0xc
	v_mov_b32_dpp v15, v11 row_ror:8 row_mask:0xf bank_mask:0xc
	v_mov_b32_dpp v8, v190 row_ror:8 row_mask:0xf bank_mask:0x3
	v_mov_b32_dpp v9, v191 row_ror:8 row_mask:0xf bank_mask:0x3
	v_mov_b32_dpp v10, v192 row_ror:8 row_mask:0xf bank_mask:0x3
	v_mov_b32_dpp v11, v193 row_ror:8 row_mask:0xf bank_mask:0x3
	s_waitcnt vmcnt(18)
	v_mul_f32_e32 v12, v12, v240
	v_mul_f32_e32 v13, v13, v240
	v_mul_f32_e32 v14, v14, v240
	v_mul_f32_e32 v15, v15, v240
	v_mul_f32_e32 v8, v8, v241
	v_mul_f32_e32 v9, v9, v241
	v_mul_f32_e32 v10, v10, v241
	v_mul_f32_e64 v11, v11, v241
	v_fma_f32 v12, v12, v132, v204
	v_fma_f32 v13, v13, v133, v205
	v_fma_f32 v14, v14, v134, v206
	v_fma_f32 v15, v15, v135, v207
	v_fma_f32 v8, v8, v132, v208
	v_fma_f32 v9, v9, v133, v209
	v_fma_f32 v10, v10, v134, v210
	v_fma_f32 v11, v11, v135, v211
	v_add_u32_e32 v252, 0xa0000, v157
	v_add_u32_e32 v253, 0xa8000, v157
	global_store_dwordx4 v252, v[12:15], s[6:7] offset:512 nt
	global_store_dwordx4 v253, v[8:11], s[6:7] offset:512 nt
	v_mov_b32_e32 v190, v20
	v_mov_b32_e32 v191, v21
	v_mov_b32_e32 v192, v22
	v_mov_b32_e32 v193, v23
	v_mov_b32_dpp v20, v16 row_ror:8 row_mask:0xf bank_mask:0xc
	v_mov_b32_dpp v21, v17 row_ror:8 row_mask:0xf bank_mask:0xc
	v_mov_b32_dpp v22, v18 row_ror:8 row_mask:0xf bank_mask:0xc
	v_mov_b32_dpp v23, v19 row_ror:8 row_mask:0xf bank_mask:0xc
	v_mov_b32_dpp v16, v190 row_ror:8 row_mask:0xf bank_mask:0x3
	v_mov_b32_dpp v17, v191 row_ror:8 row_mask:0xf bank_mask:0x3
	v_mov_b32_dpp v18, v192 row_ror:8 row_mask:0xf bank_mask:0x3
	v_mov_b32_dpp v19, v193 row_ror:8 row_mask:0xf bank_mask:0x3
	s_waitcnt vmcnt(16)
	v_mul_f32_e32 v20, v20, v242
	v_mul_f32_e32 v21, v21, v242
	v_mul_f32_e32 v22, v22, v242
	v_mul_f32_e32 v23, v23, v242
	v_mul_f32_e32 v16, v16, v243
	v_mul_f32_e32 v17, v17, v243
	v_mul_f32_e32 v18, v18, v243
	v_mul_f32_e64 v19, v19, v243
	v_fma_f32 v20, v20, v128, v212
	v_fma_f32 v21, v21, v129, v213
	v_fma_f32 v22, v22, v130, v214
	v_fma_f32 v23, v23, v131, v215
	v_fma_f32 v16, v16, v128, v216
	v_fma_f32 v17, v17, v129, v217
	v_fma_f32 v18, v18, v130, v218
	v_fma_f32 v19, v19, v131, v219
	v_add_u32_e32 v252, 0xb0000, v157
	v_add_u32_e32 v253, 0xb8000, v157
	global_store_dwordx4 v252, v[20:23], s[6:7] nt
	global_store_dwordx4 v253, v[16:19], s[6:7] nt
	v_mov_b32_e32 v190, v4
	v_mov_b32_e32 v191, v5
	v_mov_b32_e32 v192, v6
	v_mov_b32_e32 v193, v7
	v_mov_b32_dpp v4, v0 row_ror:8 row_mask:0xf bank_mask:0xc
	v_mov_b32_dpp v5, v1 row_ror:8 row_mask:0xf bank_mask:0xc
	v_mov_b32_dpp v6, v2 row_ror:8 row_mask:0xf bank_mask:0xc
	v_mov_b32_dpp v7, v3 row_ror:8 row_mask:0xf bank_mask:0xc
	v_mov_b32_dpp v0, v190 row_ror:8 row_mask:0xf bank_mask:0x3
	v_mov_b32_dpp v1, v191 row_ror:8 row_mask:0xf bank_mask:0x3
	v_mov_b32_dpp v2, v192 row_ror:8 row_mask:0xf bank_mask:0x3
	v_mov_b32_dpp v3, v193 row_ror:8 row_mask:0xf bank_mask:0x3
	s_waitcnt vmcnt(14)
	v_mul_f32_e32 v4, v4, v242
	v_mul_f32_e32 v5, v5, v242
	v_mul_f32_e32 v6, v6, v242
	v_mul_f32_e32 v7, v7, v242
	v_mul_f32_e32 v0, v0, v243
	v_mul_f32_e32 v1, v1, v243
	v_mul_f32_e32 v2, v2, v243
	v_mul_f32_e64 v3, v3, v243
	v_fma_f32 v4, v4, v132, v220
	v_fma_f32 v5, v5, v133, v221
	v_fma_f32 v6, v6, v134, v222
	v_fma_f32 v7, v7, v135, v223
	v_fma_f32 v0, v0, v132, v224
	v_fma_f32 v1, v1, v133, v225
	v_fma_f32 v2, v2, v134, v226
	v_fma_f32 v3, v3, v135, v227
	v_add_u32_e32 v252, 0xb0000, v157
	v_add_u32_e32 v253, 0xb8000, v157
	global_store_dwordx4 v252, v[4:7], s[6:7] offset:512 nt
	global_store_dwordx4 v253, v[0:3], s[6:7] offset:512 nt
	s_waitcnt lgkmcnt(0)
	s_barrier

; template <class Epi, class Sched, bool ALIGN_EPI = false, bool SP2 = false>
; __device__ __forceinline__ void gemm_phase(PG8_LAS unsigned char* lds, const Gemm g, const Sched& S, const Epi& E) {
;     ...
;         const bool has_next = S.next(ui + 1, nxt);
;         const char* nA = has_next ? (const char*)g.A + (size_t)nxt.pm * tstep : cA; const char* nB = has_next ? (const char*)g.Bt + (size_t)nxt.pn * tstep : cB;
;         for (int t = 0; t < nt; t += 2) {
;             const bool last = (t == nt - 2);
;             const char* a1 = cA + (size_t)(t + 1) * kstep;
;             const char* a2 = last ? nA : cA + (size_t)(t + 2) * kstep; const char* b2 = last ? nB : cB + (size_t)(t + 2) * kstep;
;             const char* a3 = a2 + kstep; const char* b3 = b2 + kstep;
;     ...
;         cur = nxt; cA = nA; cB = nB; ++ui;
.LBB0_1133:
	s_add_u32 s29, s34, 0x100
	s_addc_u32 s69, s35, 0
	s_add_u32 s34, s26, 0xb0080
	s_addc_u32 s35, s27, 0
	v_lshl_add_u64 v[134:135], s[34:35], 0, v[130:131]
	v_lshl_add_u64 v[136:137], s[34:35], 0, v[132:133]
	s_mov_b32 s70, -2
	s_mov_b64 s[34:35], 0
	s_nop 0
	s_nop 0
	s_nop 0
	s_nop 0
	s_nop 0
	s_nop 0
	s_nop 0
	s_nop 0
